# adaLN bias load hoisted to the top of the adaLN path; adaLN counter published right after the modulation stores are acknowledged, before the weight-copy item is finished
# speedup vs baseline: 1.0141x; 1.0021x over previous
.LBB0_55:
	v_and_b32_e32 v109, 31, v2
	v_lshl_or_b32 v8, s3, 5, v109
	s_mov_b32 s27, 0x2aaaaaab
	v_mul_hi_i32 v1, v8, s27
	v_lshrrev_b32_e32 v3, 31, v1
	v_ashrrev_i32_e32 v1, 9, v1
	v_add_u32_e32 v15, v1, v3
	s_waitcnt lgkmcnt(0)
	v_lshlrev_b32_e32 v112, 2, v0
	v_mov_b32_e32 v113, 0
	s_mov_b64 s[98:99], 0x1000
	v_lshl_add_u64 v[114:115], s[36:37], 0, v[112:113]
	v_lshl_add_u64 v[112:113], s[34:35], 0, v[112:113]
	global_load_dword v126, v[114:115], off
	global_load_dword v127, v[114:115], off offset:2048
	v_lshl_add_u64 v[114:115], v[114:115], 0, s[98:99]
	global_load_dword v128, v[114:115], off
	global_load_dword v129, v[114:115], off offset:2048
	v_lshl_add_u64 v[114:115], v[114:115], 0, s[98:99]
	global_load_dword v130, v[114:115], off
	global_load_dword v131, v[114:115], off offset:2048
	v_lshl_add_u64 v[114:115], v[114:115], 0, s[98:99]
	global_load_dword v132, v[114:115], off
	global_load_dword v133, v[114:115], off offset:2048
	v_lshl_add_u64 v[114:115], v[114:115], 0, s[98:99]
	global_load_dword v134, v[114:115], off
	global_load_dword v135, v[114:115], off offset:2048
	v_lshl_add_u64 v[114:115], v[114:115], 0, s[98:99]
	global_load_dword v136, v[114:115], off
	global_load_dword v137, v[114:115], off offset:2048
	v_lshl_add_u64 v[114:115], v[114:115], 0, s[98:99]
	global_load_dword v138, v[114:115], off
	global_load_dword v139, v[114:115], off offset:2048
	v_lshl_add_u64 v[114:115], v[114:115], 0, s[98:99]
	global_load_dword v140, v[114:115], off
	global_load_dword v141, v[114:115], off offset:2048
	global_load_dword v142, v[112:113], off
	global_load_dword v143, v[112:113], off offset:2048
	v_lshlrev_b32_e32 v114, 2, v8
	v_mov_b32_e32 v115, 0
	v_lshl_add_u64 v[114:115], s[12:13], 0, v[114:115]
	global_load_dword v144, v[114:115], off
	v_mov_b64_e32 v[4:5], s[40:41]
	s_and_b64 s[40:41], s[4:5], exec
	v_mul_i32_i24_e32 v1, 0xc00, v15
	s_mov_b32 s27, 0xc00000
	s_cselect_b32 s31, s15, s31
	s_cselect_b32 s39, s14, s30
	s_ashr_i32 s43, s42, 31
	v_sub_u32_e32 v6, v8, v1
	v_mad_i64_i32 v[4:5], s[40:41], v15, s27, v[4:5]
	s_lshl_b32 s30, s26, 6
	s_lshl_b64 s[26:27], s[42:43], 2
	v_ashrrev_i32_e32 v7, 31, v6
	v_ashrrev_i32_e32 v3, 5, v2
	s_add_u32 s26, s39, s26
	v_mov_b32_e32 v11, 0
	v_lshl_add_u64 v[12:13], v[6:7], 2, v[4:5]
	v_add_u32_e32 v1, s30, v3
	s_addc_u32 s27, s31, s27
	v_lshlrev_b32_e32 v4, 2, v109
	v_mov_b32_e32 v5, v11
	v_lshl_add_u64 v[38:39], s[26:27], 0, v[4:5]
	v_mad_i64_i32 v[16:17], s[26:27], s38, v1, 0
	v_add_u32_e32 v5, 2, v1
	v_lshl_add_u64 v[22:23], v[16:17], 2, v[38:39]
	v_mad_i64_i32 v[16:17], s[26:27], s38, v5, 0
	v_add_u32_e32 v5, 4, v1
	v_lshl_add_u64 v[24:25], v[16:17], 2, v[38:39]
	v_mad_i64_i32 v[16:17], s[26:27], s38, v5, 0
	v_add_u32_e32 v5, 6, v1
	v_lshl_add_u64 v[26:27], v[16:17], 2, v[38:39]
	v_mad_i64_i32 v[16:17], s[26:27], s38, v5, 0
	v_add_u32_e32 v5, 8, v1
	v_lshl_add_u64 v[28:29], v[16:17], 2, v[38:39]
	v_mad_i64_i32 v[16:17], s[26:27], s38, v5, 0
	v_add_u32_e32 v5, 10, v1
	v_lshl_add_u64 v[30:31], v[16:17], 2, v[38:39]
	v_mad_i64_i32 v[16:17], s[26:27], s38, v5, 0
	v_add_u32_e32 v5, 12, v1
	v_lshl_add_u64 v[32:33], v[16:17], 2, v[38:39]
	v_mad_i64_i32 v[16:17], s[26:27], s38, v5, 0
	v_add_u32_e32 v5, 14, v1
	v_lshl_add_u64 v[34:35], v[16:17], 2, v[38:39]
	v_mad_i64_i32 v[16:17], s[26:27], s38, v5, 0
	v_add_u32_e32 v9, 16, v1
	v_lshl_add_u64 v[36:37], v[16:17], 2, v[38:39]
	global_load_dword v5, v[22:23], off nt
	global_load_dword v7, v[24:25], off nt
	global_load_dword v16, v[26:27], off nt
	global_load_dword v18, v[28:29], off nt
	global_load_dword v17, v[30:31], off nt
	global_load_dword v19, v[32:33], off nt
	global_load_dword v20, v[34:35], off nt
	global_load_dword v21, v[36:37], off nt
	v_mad_i64_i32 v[22:23], s[26:27], s38, v9, 0
	v_add_u32_e32 v9, 18, v1
	v_lshl_add_u64 v[30:31], v[22:23], 2, v[38:39]
	v_mad_i64_i32 v[22:23], s[26:27], s38, v9, 0
	v_add_u32_e32 v9, 20, v1
	v_lshl_add_u64 v[32:33], v[22:23], 2, v[38:39]
	v_mad_i64_i32 v[22:23], s[26:27], s38, v9, 0
	v_add_u32_e32 v9, 22, v1
	v_lshl_add_u64 v[34:35], v[22:23], 2, v[38:39]
	v_mad_i64_i32 v[22:23], s[26:27], s38, v9, 0
	v_add_u32_e32 v9, 24, v1
	v_lshl_add_u64 v[36:37], v[22:23], 2, v[38:39]
	v_mad_i64_i32 v[22:23], s[26:27], s38, v9, 0
	v_add_u32_e32 v9, 26, v1
	v_lshl_add_u64 v[40:41], v[22:23], 2, v[38:39]
	v_mad_i64_i32 v[22:23], s[26:27], s38, v9, 0
	v_add_u32_e32 v9, 28, v1
	v_lshl_add_u64 v[42:43], v[22:23], 2, v[38:39]
	v_mad_i64_i32 v[22:23], s[26:27], s38, v9, 0
	v_add_u32_e32 v9, 30, v1
	v_lshl_add_u64 v[44:45], v[22:23], 2, v[38:39]
	v_mad_i64_i32 v[22:23], s[26:27], s38, v9, 0
	v_add_u32_e32 v9, 32, v1
	v_lshl_add_u64 v[46:47], v[22:23], 2, v[38:39]
	global_load_dword v22, v[30:31], off nt
	global_load_dword v23, v[32:33], off nt
	global_load_dword v24, v[34:35], off nt
	global_load_dword v26, v[36:37], off nt
	global_load_dword v25, v[40:41], off nt
	global_load_dword v27, v[42:43], off nt
	global_load_dword v28, v[44:45], off nt
	global_load_dword v29, v[46:47], off nt
	v_mad_i64_i32 v[30:31], s[26:27], s38, v9, 0
	v_add_u32_e32 v9, 34, v1
	v_lshl_add_u64 v[40:41], v[30:31], 2, v[38:39]
	v_mad_i64_i32 v[30:31], s[26:27], s38, v9, 0
	v_add_u32_e32 v9, 36, v1
	v_lshl_add_u64 v[42:43], v[30:31], 2, v[38:39]
	v_mad_i64_i32 v[30:31], s[26:27], s38, v9, 0
	v_add_u32_e32 v9, 38, v1
	v_lshl_add_u64 v[44:45], v[30:31], 2, v[38:39]
	v_mad_i64_i32 v[30:31], s[26:27], s38, v9, 0
	v_add_u32_e32 v9, 40, v1
	v_lshl_add_u64 v[46:47], v[30:31], 2, v[38:39]
	v_mad_i64_i32 v[30:31], s[26:27], s38, v9, 0
	v_add_u32_e32 v9, 42, v1
	v_lshl_add_u64 v[48:49], v[30:31], 2, v[38:39]
	v_mad_i64_i32 v[30:31], s[26:27], s38, v9, 0
	v_add_u32_e32 v9, 44, v1
	v_lshl_add_u64 v[50:51], v[30:31], 2, v[38:39]
	v_mad_i64_i32 v[30:31], s[26:27], s38, v9, 0
	v_add_u32_e32 v9, 46, v1
	v_lshl_add_u64 v[52:53], v[30:31], 2, v[38:39]
	v_mad_i64_i32 v[30:31], s[26:27], s38, v9, 0
	v_add_u32_e32 v9, 48, v1
	v_lshl_add_u64 v[54:55], v[30:31], 2, v[38:39]
	global_load_dword v30, v[40:41], off nt
	global_load_dword v31, v[42:43], off nt
	global_load_dword v32, v[44:45], off nt
	global_load_dword v34, v[46:47], off nt
	global_load_dword v33, v[48:49], off nt
	global_load_dword v35, v[50:51], off nt
	global_load_dword v36, v[52:53], off nt
	global_load_dword v37, v[54:55], off nt
	v_mad_i64_i32 v[40:41], s[26:27], s38, v9, 0
	v_add_u32_e32 v9, 50, v1
	v_lshl_add_u64 v[46:47], v[40:41], 2, v[38:39]
	v_mad_i64_i32 v[40:41], s[26:27], s38, v9, 0
	v_add_u32_e32 v9, 52, v1
	v_lshl_add_u64 v[48:49], v[40:41], 2, v[38:39]
	v_mad_i64_i32 v[40:41], s[26:27], s38, v9, 0
	v_add_u32_e32 v9, 54, v1
	v_lshl_add_u64 v[50:51], v[40:41], 2, v[38:39]
	v_mad_i64_i32 v[40:41], s[26:27], s38, v9, 0
	v_add_u32_e32 v9, 56, v1
	v_lshl_add_u64 v[52:53], v[40:41], 2, v[38:39]
	v_mad_i64_i32 v[40:41], s[26:27], s38, v9, 0
	v_add_u32_e32 v9, 58, v1
	v_lshl_add_u64 v[54:55], v[40:41], 2, v[38:39]
	v_mad_i64_i32 v[40:41], s[26:27], s38, v9, 0
	v_add_u32_e32 v9, 60, v1
	v_ashrrev_i32_e32 v14, 5, v0
	v_lshl_add_u64 v[56:57], v[40:41], 2, v[38:39]
	v_mad_i64_i32 v[40:41], s[26:27], s38, v9, 0
	v_add_u32_e32 v1, 62, v1
	v_lshl_add_u64 v[58:59], v[40:41], 2, v[38:39]
	v_mad_i64_i32 v[40:41], s[26:27], s38, v1, 0
	v_lshlrev_b32_e32 v1, 6, v14
	s_movk_i32 s26, 0x3000
	v_or_b32_e32 v9, 1, v1
	v_lshl_add_u64 v[60:61], v[40:41], 2, v[38:39]
	global_load_dword v38, v[46:47], off nt
	global_load_dword v39, v[48:49], off nt
	global_load_dword v40, v[50:51], off nt
	global_load_dword v42, v[52:53], off nt
	global_load_dword v41, v[54:55], off nt
	global_load_dword v43, v[56:57], off nt
	global_load_dword v44, v[58:59], off nt
	global_load_dword v45, v[60:61], off nt
	v_mad_i64_i32 v[56:57], s[38:39], v9, s26, v[12:13]
	v_or_b32_e32 v9, 2, v1
	v_mad_i64_i32 v[58:59], s[38:39], v9, s26, v[12:13]
	v_or_b32_e32 v9, 3, v1
	v_mad_i64_i32 v[60:61], s[38:39], v9, s26, v[12:13]
	v_or_b32_e32 v9, 4, v1
	v_mad_i64_i32 v[62:63], s[38:39], v9, s26, v[12:13]
	v_or_b32_e32 v9, 5, v1
	v_mad_i64_i32 v[64:65], s[38:39], v9, s26, v[12:13]
	v_or_b32_e32 v9, 6, v1
	v_mad_i64_i32 v[54:55], s[38:39], v1, s26, v[12:13]
	v_mad_i64_i32 v[66:67], s[38:39], v9, s26, v[12:13]
	v_or_b32_e32 v9, 7, v1
	v_or_b32_e32 v10, 8, v1
	v_mad_i64_i32 v[68:69], s[38:39], v9, s26, v[12:13]
	global_load_dword v50, v[54:55], off nt
	global_load_dword v52, v[56:57], off nt
	global_load_dword v51, v[58:59], off nt
	global_load_dword v48, v[60:61], off nt
	global_load_dword v46, v[62:63], off nt
	global_load_dword v49, v[64:65], off nt
	global_load_dword v47, v[66:67], off nt
	global_load_dword v9, v[68:69], off nt
	v_mad_i64_i32 v[62:63], s[38:39], v10, s26, v[12:13]
	v_or_b32_e32 v10, 9, v1
	v_mad_i64_i32 v[64:65], s[38:39], v10, s26, v[12:13]
	v_or_b32_e32 v10, 10, v1
	v_mad_i64_i32 v[66:67], s[38:39], v10, s26, v[12:13]
	v_or_b32_e32 v10, 11, v1
	v_mad_i64_i32 v[68:69], s[38:39], v10, s26, v[12:13]
	v_or_b32_e32 v10, 12, v1
	v_mad_i64_i32 v[70:71], s[38:39], v10, s26, v[12:13]
	v_or_b32_e32 v10, 13, v1
	v_mad_i64_i32 v[72:73], s[38:39], v10, s26, v[12:13]
	v_or_b32_e32 v10, 14, v1
	v_mad_i64_i32 v[74:75], s[38:39], v10, s26, v[12:13]
	v_or_b32_e32 v10, 15, v1
	v_mad_i64_i32 v[76:77], s[38:39], v10, s26, v[12:13]
	v_or_b32_e32 v10, 16, v1
	global_load_dword v58, v[62:63], off nt
	global_load_dword v60, v[64:65], off nt
	global_load_dword v59, v[66:67], off nt
	global_load_dword v56, v[68:69], off nt
	global_load_dword v55, v[70:71], off nt
	global_load_dword v57, v[72:73], off nt
	global_load_dword v53, v[74:75], off nt
	global_load_dword v54, v[76:77], off nt
	v_mad_i64_i32 v[70:71], s[38:39], v10, s26, v[12:13]
	v_or_b32_e32 v10, 17, v1
	v_mad_i64_i32 v[72:73], s[38:39], v10, s26, v[12:13]
	v_or_b32_e32 v10, 18, v1
	v_mad_i64_i32 v[74:75], s[38:39], v10, s26, v[12:13]
	v_or_b32_e32 v10, 19, v1
	v_mad_i64_i32 v[76:77], s[38:39], v10, s26, v[12:13]
	v_or_b32_e32 v10, 20, v1
	v_mad_i64_i32 v[78:79], s[38:39], v10, s26, v[12:13]
	v_or_b32_e32 v10, 21, v1
	v_mad_i64_i32 v[80:81], s[38:39], v10, s26, v[12:13]
	v_or_b32_e32 v10, 22, v1
	v_mad_i64_i32 v[82:83], s[38:39], v10, s26, v[12:13]
	v_or_b32_e32 v10, 23, v1
	v_mad_i64_i32 v[84:85], s[38:39], v10, s26, v[12:13]
	v_or_b32_e32 v10, 24, v1
	global_load_dword v64, v[70:71], off nt
	global_load_dword v68, v[72:73], off nt
	global_load_dword v65, v[74:75], off nt
	global_load_dword v66, v[76:77], off nt
	global_load_dword v63, v[78:79], off nt
	global_load_dword v67, v[80:81], off nt
	global_load_dword v61, v[82:83], off nt
	global_load_dword v62, v[84:85], off nt
	v_mad_i64_i32 v[78:79], s[38:39], v10, s26, v[12:13]
	v_or_b32_e32 v10, 25, v1
	v_mad_i64_i32 v[80:81], s[38:39], v10, s26, v[12:13]
	v_or_b32_e32 v10, 26, v1
	v_mad_i64_i32 v[82:83], s[38:39], v10, s26, v[12:13]
	v_or_b32_e32 v10, 27, v1
	v_mad_i64_i32 v[84:85], s[38:39], v10, s26, v[12:13]
	v_or_b32_e32 v10, 28, v1
	v_mad_i64_i32 v[86:87], s[38:39], v10, s26, v[12:13]
	v_or_b32_e32 v10, 29, v1
	v_mad_i64_i32 v[88:89], s[38:39], v10, s26, v[12:13]
	v_or_b32_e32 v10, 30, v1
	v_mad_i64_i32 v[90:91], s[38:39], v10, s26, v[12:13]
	v_or_b32_e32 v10, 31, v1
	v_mad_i64_i32 v[92:93], s[38:39], v10, s26, v[12:13]
	v_or_b32_e32 v10, 32, v1
	global_load_dword v72, v[78:79], off nt
	global_load_dword v76, v[80:81], off nt
	global_load_dword v73, v[82:83], off nt
	global_load_dword v74, v[84:85], off nt
	global_load_dword v71, v[86:87], off nt
	global_load_dword v75, v[88:89], off nt
	global_load_dword v69, v[90:91], off nt
	global_load_dword v70, v[92:93], off nt
	v_mad_i64_i32 v[86:87], s[38:39], v10, s26, v[12:13]
	v_or_b32_e32 v10, 33, v1
	v_mad_i64_i32 v[88:89], s[38:39], v10, s26, v[12:13]
	v_or_b32_e32 v10, 34, v1
	v_mad_i64_i32 v[90:91], s[38:39], v10, s26, v[12:13]
	v_or_b32_e32 v10, 35, v1
	v_mad_i64_i32 v[92:93], s[38:39], v10, s26, v[12:13]
	v_or_b32_e32 v10, 36, v1
	v_mad_i64_i32 v[94:95], s[38:39], v10, s26, v[12:13]
	v_or_b32_e32 v10, 37, v1
	v_mad_i64_i32 v[96:97], s[38:39], v10, s26, v[12:13]
	v_or_b32_e32 v10, 38, v1
	v_mad_i64_i32 v[98:99], s[38:39], v10, s26, v[12:13]
	v_or_b32_e32 v10, 39, v1
	v_mad_i64_i32 v[100:101], s[38:39], v10, s26, v[12:13]
	v_or_b32_e32 v10, 40, v1
	global_load_dword v80, v[86:87], off nt
	global_load_dword v84, v[88:89], off nt
	global_load_dword v81, v[90:91], off nt
	global_load_dword v82, v[92:93], off nt
	global_load_dword v79, v[94:95], off nt
	global_load_dword v83, v[96:97], off nt
	global_load_dword v77, v[98:99], off nt
	global_load_dword v78, v[100:101], off nt
	v_mad_i64_i32 v[94:95], s[38:39], v10, s26, v[12:13]
	v_or_b32_e32 v10, 41, v1
	v_mad_i64_i32 v[96:97], s[38:39], v10, s26, v[12:13]
	v_or_b32_e32 v10, 42, v1
	v_mad_i64_i32 v[98:99], s[38:39], v10, s26, v[12:13]
	v_or_b32_e32 v10, 43, v1
	v_mad_i64_i32 v[100:101], s[38:39], v10, s26, v[12:13]
	v_or_b32_e32 v10, 44, v1
	v_mad_i64_i32 v[102:103], s[38:39], v10, s26, v[12:13]
	v_or_b32_e32 v10, 45, v1
	v_mad_i64_i32 v[104:105], s[38:39], v10, s26, v[12:13]
	v_or_b32_e32 v10, 46, v1
	v_mad_i64_i32 v[106:107], s[38:39], v10, s26, v[12:13]
	v_or_b32_e32 v10, 47, v1
	v_mad_i64_i32 v[110:111], s[38:39], v10, s26, v[12:13]
	v_or_b32_e32 v10, 48, v1
	global_load_dword v88, v[94:95], off nt
	global_load_dword v92, v[96:97], off nt
	global_load_dword v89, v[98:99], off nt
	global_load_dword v90, v[100:101], off nt
	global_load_dword v87, v[102:103], off nt
	global_load_dword v91, v[104:105], off nt
	global_load_dword v85, v[106:107], off nt
	global_load_dword v86, v[110:111], off nt
	v_mad_i64_i32 v[102:103], s[38:39], v10, s26, v[12:13]
	v_or_b32_e32 v10, 49, v1
	v_mad_i64_i32 v[104:105], s[38:39], v10, s26, v[12:13]
	v_or_b32_e32 v10, 50, v1
	v_mad_i64_i32 v[106:107], s[38:39], v10, s26, v[12:13]
	v_or_b32_e32 v10, 51, v1
	v_mad_i64_i32 v[110:111], s[38:39], v10, s26, v[12:13]
	v_or_b32_e32 v10, 52, v1
	v_mad_i64_i32 v[112:113], s[38:39], v10, s26, v[12:13]
	v_or_b32_e32 v10, 53, v1
	v_mad_i64_i32 v[114:115], s[38:39], v10, s26, v[12:13]
	v_or_b32_e32 v10, 54, v1
	v_mad_i64_i32 v[116:117], s[38:39], v10, s26, v[12:13]
	v_or_b32_e32 v10, 55, v1
	v_mad_i64_i32 v[118:119], s[38:39], v10, s26, v[12:13]
	v_or_b32_e32 v10, 56, v1
	global_load_dword v96, v[102:103], off nt
	global_load_dword v100, v[104:105], off nt
	global_load_dword v97, v[106:107], off nt
	global_load_dword v98, v[110:111], off nt
	global_load_dword v95, v[112:113], off nt
	global_load_dword v99, v[114:115], off nt
	global_load_dword v93, v[116:117], off nt
	global_load_dword v94, v[118:119], off nt
	v_or_b32_e32 v101, 57, v1
	v_or_b32_e32 v102, 58, v1
	v_or_b32_e32 v103, 59, v1
	v_or_b32_e32 v104, 60, v1
	v_or_b32_e32 v105, 61, v1
	v_or_b32_e32 v106, 62, v1
	v_or_b32_e32 v1, 63, v1
	v_mad_i64_i32 v[110:111], s[38:39], v10, s26, v[12:13]
	v_mad_i64_i32 v[112:113], s[38:39], v101, s26, v[12:13]
	v_mad_i64_i32 v[114:115], s[38:39], v102, s26, v[12:13]
	v_mad_i64_i32 v[116:117], s[38:39], v103, s26, v[12:13]
	v_mad_i64_i32 v[118:119], s[38:39], v104, s26, v[12:13]
	v_mad_i64_i32 v[120:121], s[38:39], v105, s26, v[12:13]
	v_mad_i64_i32 v[122:123], s[38:39], v106, s26, v[12:13]
	v_mad_i64_i32 v[12:13], s[26:27], v1, s26, v[12:13]
	global_load_dword v104, v[110:111], off nt
	global_load_dword v108, v[112:113], off nt
	global_load_dword v105, v[114:115], off nt
	global_load_dword v106, v[116:117], off nt
	global_load_dword v102, v[118:119], off nt
	global_load_dword v107, v[120:121], off nt
	global_load_dword v103, v[122:123], off nt
	global_load_dword v101, v[12:13], off nt
	s_movk_i32 s26, 0x2400
	v_cmp_gt_i32_e32 vcc, s26, v0
	s_and_saveexec_b64 s[38:39], vcc
	s_cbranch_execz .LBB0_58
	s_lshl_b32 s26, s75, 8
	v_lshl_add_u32 v110, v2, 2, s26
	s_waitcnt vmcnt(63)
	v_mul_f32_e32 v111, 0xbfb8aa3b, v126
	v_exp_f32_e32 v111, v111
	s_nop 0
	v_add_f32_e32 v111, 1.0, v111
	v_div_scale_f32 v112, s[42:43], v111, v111, v126
	v_rcp_f32_e32 v113, v112
	v_div_scale_f32 v114, vcc, v126, v111, v126
	v_fma_f32 v115, -v112, v113, 1.0
	v_fmac_f32_e32 v113, v115, v113
	v_mul_f32_e32 v115, v114, v113
	v_fma_f32 v116, -v112, v115, v114
	v_fmac_f32_e32 v115, v116, v113
	v_fma_f32 v112, -v112, v115, v114
	v_div_fmas_f32 v112, v112, v113, v115
	v_div_fixup_f32 v10, v112, v111, v126
	ds_write_b32 v110, v10
	v_mul_f32_e32 v111, 0xbfb8aa3b, v127
	v_exp_f32_e32 v111, v111
	s_nop 0
	v_add_f32_e32 v111, 1.0, v111
	v_div_scale_f32 v112, s[42:43], v111, v111, v127
	v_rcp_f32_e32 v113, v112
	v_div_scale_f32 v114, vcc, v127, v111, v127
	v_fma_f32 v115, -v112, v113, 1.0
	v_fmac_f32_e32 v113, v115, v113
	v_mul_f32_e32 v115, v114, v113
	v_fma_f32 v116, -v112, v115, v114
	v_fmac_f32_e32 v115, v116, v113
	v_fma_f32 v112, -v112, v115, v114
	v_div_fmas_f32 v112, v112, v113, v115
	v_div_fixup_f32 v10, v112, v111, v127
	ds_write_b32 v110, v10 offset:2048
	v_mul_f32_e32 v111, 0xbfb8aa3b, v128
	v_exp_f32_e32 v111, v111
	s_nop 0
	v_add_f32_e32 v111, 1.0, v111
	v_div_scale_f32 v112, s[42:43], v111, v111, v128
	v_rcp_f32_e32 v113, v112
	v_div_scale_f32 v114, vcc, v128, v111, v128
	v_fma_f32 v115, -v112, v113, 1.0
	v_fmac_f32_e32 v113, v115, v113
	v_mul_f32_e32 v115, v114, v113
	v_fma_f32 v116, -v112, v115, v114
	v_fmac_f32_e32 v115, v116, v113
	v_fma_f32 v112, -v112, v115, v114
	v_div_fmas_f32 v112, v112, v113, v115
	v_div_fixup_f32 v10, v112, v111, v128
	ds_write_b32 v110, v10 offset:4096
	v_mul_f32_e32 v111, 0xbfb8aa3b, v129
	v_exp_f32_e32 v111, v111
	s_nop 0
	v_add_f32_e32 v111, 1.0, v111
	v_div_scale_f32 v112, s[42:43], v111, v111, v129
	v_rcp_f32_e32 v113, v112
	v_div_scale_f32 v114, vcc, v129, v111, v129
	v_fma_f32 v115, -v112, v113, 1.0
	v_fmac_f32_e32 v113, v115, v113
	v_mul_f32_e32 v115, v114, v113
	v_fma_f32 v116, -v112, v115, v114
	v_fmac_f32_e32 v115, v116, v113
	v_fma_f32 v112, -v112, v115, v114
	v_div_fmas_f32 v112, v112, v113, v115
	v_div_fixup_f32 v10, v112, v111, v129
	ds_write_b32 v110, v10 offset:6144
	v_mul_f32_e32 v111, 0xbfb8aa3b, v130
	v_exp_f32_e32 v111, v111
	s_nop 0
	v_add_f32_e32 v111, 1.0, v111
	v_div_scale_f32 v112, s[42:43], v111, v111, v130
	v_rcp_f32_e32 v113, v112
	v_div_scale_f32 v114, vcc, v130, v111, v130
	v_fma_f32 v115, -v112, v113, 1.0
	v_fmac_f32_e32 v113, v115, v113
	v_mul_f32_e32 v115, v114, v113
	v_fma_f32 v116, -v112, v115, v114
	v_fmac_f32_e32 v115, v116, v113
	v_fma_f32 v112, -v112, v115, v114
	v_div_fmas_f32 v112, v112, v113, v115
	v_div_fixup_f32 v10, v112, v111, v130
	ds_write_b32 v110, v10 offset:8192
	v_mul_f32_e32 v111, 0xbfb8aa3b, v131
	v_exp_f32_e32 v111, v111
	s_nop 0
	v_add_f32_e32 v111, 1.0, v111
	v_div_scale_f32 v112, s[42:43], v111, v111, v131
	v_rcp_f32_e32 v113, v112
	v_div_scale_f32 v114, vcc, v131, v111, v131
	v_fma_f32 v115, -v112, v113, 1.0
	v_fmac_f32_e32 v113, v115, v113
	v_mul_f32_e32 v115, v114, v113
	v_fma_f32 v116, -v112, v115, v114
	v_fmac_f32_e32 v115, v116, v113
	v_fma_f32 v112, -v112, v115, v114
	v_div_fmas_f32 v112, v112, v113, v115
	v_div_fixup_f32 v10, v112, v111, v131
	ds_write_b32 v110, v10 offset:10240
	v_mul_f32_e32 v111, 0xbfb8aa3b, v132
	v_exp_f32_e32 v111, v111
	s_nop 0
	v_add_f32_e32 v111, 1.0, v111
	v_div_scale_f32 v112, s[42:43], v111, v111, v132
	v_rcp_f32_e32 v113, v112
	v_div_scale_f32 v114, vcc, v132, v111, v132
	v_fma_f32 v115, -v112, v113, 1.0
	v_fmac_f32_e32 v113, v115, v113
	v_mul_f32_e32 v115, v114, v113
	v_fma_f32 v116, -v112, v115, v114
	v_fmac_f32_e32 v115, v116, v113
	v_fma_f32 v112, -v112, v115, v114
	v_div_fmas_f32 v112, v112, v113, v115
	v_div_fixup_f32 v10, v112, v111, v132
	ds_write_b32 v110, v10 offset:12288
	v_mul_f32_e32 v111, 0xbfb8aa3b, v133
	v_exp_f32_e32 v111, v111
	s_nop 0
	v_add_f32_e32 v111, 1.0, v111
	v_div_scale_f32 v112, s[42:43], v111, v111, v133
	v_rcp_f32_e32 v113, v112
	v_div_scale_f32 v114, vcc, v133, v111, v133
	v_fma_f32 v115, -v112, v113, 1.0
	v_fmac_f32_e32 v113, v115, v113
	v_mul_f32_e32 v115, v114, v113
	v_fma_f32 v116, -v112, v115, v114
	v_fmac_f32_e32 v115, v116, v113
	v_fma_f32 v112, -v112, v115, v114
	v_div_fmas_f32 v112, v112, v113, v115
	v_div_fixup_f32 v10, v112, v111, v133
	ds_write_b32 v110, v10 offset:14336
	v_mul_f32_e32 v111, 0xbfb8aa3b, v134
	v_exp_f32_e32 v111, v111
	s_nop 0
	v_add_f32_e32 v111, 1.0, v111
	v_div_scale_f32 v112, s[42:43], v111, v111, v134
	v_rcp_f32_e32 v113, v112
	v_div_scale_f32 v114, vcc, v134, v111, v134
	v_fma_f32 v115, -v112, v113, 1.0
	v_fmac_f32_e32 v113, v115, v113
	v_mul_f32_e32 v115, v114, v113
	v_fma_f32 v116, -v112, v115, v114
	v_fmac_f32_e32 v115, v116, v113
	v_fma_f32 v112, -v112, v115, v114
	v_div_fmas_f32 v112, v112, v113, v115
	v_div_fixup_f32 v10, v112, v111, v134
	ds_write_b32 v110, v10 offset:16384
	v_mul_f32_e32 v111, 0xbfb8aa3b, v135
	v_exp_f32_e32 v111, v111
	s_nop 0
	v_add_f32_e32 v111, 1.0, v111
	v_div_scale_f32 v112, s[42:43], v111, v111, v135
	v_rcp_f32_e32 v113, v112
	v_div_scale_f32 v114, vcc, v135, v111, v135
	v_fma_f32 v115, -v112, v113, 1.0
	v_fmac_f32_e32 v113, v115, v113
	v_mul_f32_e32 v115, v114, v113
	v_fma_f32 v116, -v112, v115, v114
	v_fmac_f32_e32 v115, v116, v113
	v_fma_f32 v112, -v112, v115, v114
	v_div_fmas_f32 v112, v112, v113, v115
	v_div_fixup_f32 v10, v112, v111, v135
	ds_write_b32 v110, v10 offset:18432
	v_mul_f32_e32 v111, 0xbfb8aa3b, v136
	v_exp_f32_e32 v111, v111
	s_nop 0
	v_add_f32_e32 v111, 1.0, v111
	v_div_scale_f32 v112, s[42:43], v111, v111, v136
	v_rcp_f32_e32 v113, v112
	v_div_scale_f32 v114, vcc, v136, v111, v136
	v_fma_f32 v115, -v112, v113, 1.0
	v_fmac_f32_e32 v113, v115, v113
	v_mul_f32_e32 v115, v114, v113
	v_fma_f32 v116, -v112, v115, v114
	v_fmac_f32_e32 v115, v116, v113
	v_fma_f32 v112, -v112, v115, v114
	v_div_fmas_f32 v112, v112, v113, v115
	v_div_fixup_f32 v10, v112, v111, v136
	ds_write_b32 v110, v10 offset:20480
	v_mul_f32_e32 v111, 0xbfb8aa3b, v137
	v_exp_f32_e32 v111, v111
	s_nop 0
	v_add_f32_e32 v111, 1.0, v111
	v_div_scale_f32 v112, s[42:43], v111, v111, v137
	v_rcp_f32_e32 v113, v112
	v_div_scale_f32 v114, vcc, v137, v111, v137
	v_fma_f32 v115, -v112, v113, 1.0
	v_fmac_f32_e32 v113, v115, v113
	v_mul_f32_e32 v115, v114, v113
	v_fma_f32 v116, -v112, v115, v114
	v_fmac_f32_e32 v115, v116, v113
	v_fma_f32 v112, -v112, v115, v114
	v_div_fmas_f32 v112, v112, v113, v115
	v_div_fixup_f32 v10, v112, v111, v137
	ds_write_b32 v110, v10 offset:22528
	v_mul_f32_e32 v111, 0xbfb8aa3b, v138
	v_exp_f32_e32 v111, v111
	s_nop 0
	v_add_f32_e32 v111, 1.0, v111
	v_div_scale_f32 v112, s[42:43], v111, v111, v138
	v_rcp_f32_e32 v113, v112
	v_div_scale_f32 v114, vcc, v138, v111, v138
	v_fma_f32 v115, -v112, v113, 1.0
	v_fmac_f32_e32 v113, v115, v113
	v_mul_f32_e32 v115, v114, v113
	v_fma_f32 v116, -v112, v115, v114
	v_fmac_f32_e32 v115, v116, v113
	v_fma_f32 v112, -v112, v115, v114
	v_div_fmas_f32 v112, v112, v113, v115
	v_div_fixup_f32 v10, v112, v111, v138
	ds_write_b32 v110, v10 offset:24576
	v_mul_f32_e32 v111, 0xbfb8aa3b, v139
	v_exp_f32_e32 v111, v111
	s_nop 0
	v_add_f32_e32 v111, 1.0, v111
	v_div_scale_f32 v112, s[42:43], v111, v111, v139
	v_rcp_f32_e32 v113, v112
	v_div_scale_f32 v114, vcc, v139, v111, v139
	v_fma_f32 v115, -v112, v113, 1.0
	v_fmac_f32_e32 v113, v115, v113
	v_mul_f32_e32 v115, v114, v113
	v_fma_f32 v116, -v112, v115, v114
	v_fmac_f32_e32 v115, v116, v113
	v_fma_f32 v112, -v112, v115, v114
	v_div_fmas_f32 v112, v112, v113, v115
	v_div_fixup_f32 v10, v112, v111, v139
	ds_write_b32 v110, v10 offset:26624
	v_mul_f32_e32 v111, 0xbfb8aa3b, v140
	v_exp_f32_e32 v111, v111
	s_nop 0
	v_add_f32_e32 v111, 1.0, v111
	v_div_scale_f32 v112, s[42:43], v111, v111, v140
	v_rcp_f32_e32 v113, v112
	v_div_scale_f32 v114, vcc, v140, v111, v140
	v_fma_f32 v115, -v112, v113, 1.0
	v_fmac_f32_e32 v113, v115, v113
	v_mul_f32_e32 v115, v114, v113
	v_fma_f32 v116, -v112, v115, v114
	v_fmac_f32_e32 v115, v116, v113
	v_fma_f32 v112, -v112, v115, v114
	v_div_fmas_f32 v112, v112, v113, v115
	v_div_fixup_f32 v10, v112, v111, v140
	ds_write_b32 v110, v10 offset:28672
	v_mul_f32_e32 v111, 0xbfb8aa3b, v141
	v_exp_f32_e32 v111, v111
	s_nop 0
	v_add_f32_e32 v111, 1.0, v111
	v_div_scale_f32 v112, s[42:43], v111, v111, v141
	v_rcp_f32_e32 v113, v112
	v_div_scale_f32 v114, vcc, v141, v111, v141
	v_fma_f32 v115, -v112, v113, 1.0
	v_fmac_f32_e32 v113, v115, v113
	v_mul_f32_e32 v115, v114, v113
	v_fma_f32 v116, -v112, v115, v114
	v_fmac_f32_e32 v115, v116, v113
	v_fma_f32 v112, -v112, v115, v114
	v_div_fmas_f32 v112, v112, v113, v115
	v_div_fixup_f32 v10, v112, v111, v141
	ds_write_b32 v110, v10 offset:30720
	v_mul_f32_e32 v111, 0xbfb8aa3b, v142
	v_exp_f32_e32 v111, v111
	s_nop 0
	v_add_f32_e32 v111, 1.0, v111
	v_div_scale_f32 v112, s[42:43], v111, v111, v142
	v_rcp_f32_e32 v113, v112
	v_div_scale_f32 v114, vcc, v142, v111, v142
	v_fma_f32 v115, -v112, v113, 1.0
	v_fmac_f32_e32 v113, v115, v113
	v_mul_f32_e32 v115, v114, v113
	v_fma_f32 v116, -v112, v115, v114
	v_fmac_f32_e32 v115, v116, v113
	v_fma_f32 v112, -v112, v115, v114
	v_div_fmas_f32 v112, v112, v113, v115
	v_div_fixup_f32 v10, v112, v111, v142
	ds_write_b32 v110, v10 offset:32768
	v_mul_f32_e32 v111, 0xbfb8aa3b, v143
	v_exp_f32_e32 v111, v111
	s_nop 0
	v_add_f32_e32 v111, 1.0, v111
	v_div_scale_f32 v112, s[42:43], v111, v111, v143
	v_rcp_f32_e32 v113, v112
	v_div_scale_f32 v114, vcc, v143, v111, v143
	v_fma_f32 v115, -v112, v113, 1.0
	v_fmac_f32_e32 v113, v115, v113
	v_mul_f32_e32 v115, v114, v113
	v_fma_f32 v116, -v112, v115, v114
	v_fmac_f32_e32 v115, v116, v113
	v_fma_f32 v112, -v112, v115, v114
	v_div_fmas_f32 v112, v112, v113, v115
	v_div_fixup_f32 v10, v112, v111, v143
	ds_write_b32 v110, v10 offset:34816
.LBB0_58:
	s_or_b64 exec, exec, s[38:39]
	v_lshl_add_u32 v1, v14, 8, 0
	s_waitcnt lgkmcnt(0)
	s_barrier
	ds_read_b128 v[110:113], v1
	ds_read_b128 v[114:117], v1 offset:16
	ds_read_b128 v[118:121], v1 offset:32
	ds_read_b128 v[122:125], v1 offset:48
	v_lshl_add_u32 v10, v109, 2, 0
	s_movk_i32 s26, 0x480
	s_waitcnt vmcnt(58) lgkmcnt(2)
	v_mul_f32_e32 v12, v49, v115
	v_mul_f32_e32 v11, v52, v111
	v_fmac_f32_e32 v11, v50, v110
	v_fmac_f32_e32 v11, v51, v112
	v_fmac_f32_e32 v12, v46, v114
	v_fmac_f32_e32 v11, v48, v113
	s_waitcnt vmcnt(57)
	v_fmac_f32_e32 v12, v47, v116
	v_add_f32_e32 v11, 0, v11
	s_waitcnt vmcnt(56)
	v_fmac_f32_e32 v12, v9, v117
	v_add_f32_e32 v11, v11, v12
	s_waitcnt vmcnt(54) lgkmcnt(1)
	v_mul_f32_e32 v12, v60, v119
	v_fmac_f32_e32 v12, v58, v118
	s_waitcnt vmcnt(53)
	v_fmac_f32_e32 v12, v59, v120
	s_waitcnt vmcnt(52)
	v_fmac_f32_e32 v12, v56, v121
	ds_read_b128 v[110:113], v1 offset:64
	ds_read_b128 v[114:117], v1 offset:80
	v_add_f32_e32 v11, v11, v12
	s_waitcnt vmcnt(50) lgkmcnt(2)
	v_mul_f32_e32 v12, v57, v123
	v_fmac_f32_e32 v12, v55, v122
	s_waitcnt vmcnt(49)
	v_fmac_f32_e32 v12, v53, v124
	s_waitcnt vmcnt(48)
	v_fmac_f32_e32 v12, v54, v125
	v_add_f32_e32 v11, v11, v12
	s_waitcnt vmcnt(46) lgkmcnt(1)
	v_mul_f32_e32 v12, v68, v111
	v_fmac_f32_e32 v12, v64, v110
	s_waitcnt vmcnt(45)
	v_fmac_f32_e32 v12, v65, v112
	s_waitcnt vmcnt(44)
	v_fmac_f32_e32 v12, v66, v113
	ds_read_b128 v[110:113], v1 offset:96
	v_add_f32_e32 v11, v11, v12
	s_waitcnt vmcnt(42) lgkmcnt(1)
	v_mul_f32_e32 v12, v67, v115
	v_fmac_f32_e32 v12, v63, v114
	s_waitcnt vmcnt(41)
	v_fmac_f32_e32 v12, v61, v116
	s_waitcnt vmcnt(40)
	v_fmac_f32_e32 v12, v62, v117
	ds_read_b128 v[114:117], v1 offset:112
	v_add_f32_e32 v11, v11, v12
	s_waitcnt vmcnt(38) lgkmcnt(1)
	v_mul_f32_e32 v12, v76, v111
	v_fmac_f32_e32 v12, v72, v110
	s_waitcnt vmcnt(37)
	v_fmac_f32_e32 v12, v73, v112
	s_waitcnt vmcnt(36)
	v_fmac_f32_e32 v12, v74, v113
	ds_read_b128 v[110:113], v1 offset:128
	v_add_f32_e32 v11, v11, v12
	s_waitcnt vmcnt(34) lgkmcnt(1)
	v_mul_f32_e32 v12, v75, v115
	v_fmac_f32_e32 v12, v71, v114
	s_waitcnt vmcnt(33)
	v_fmac_f32_e32 v12, v69, v116
	s_waitcnt vmcnt(32)
	v_fmac_f32_e32 v12, v70, v117
	ds_read_b128 v[114:117], v1 offset:144
	v_add_f32_e32 v11, v11, v12
	s_waitcnt vmcnt(30) lgkmcnt(1)
	v_mul_f32_e32 v12, v84, v111
	v_fmac_f32_e32 v12, v80, v110
	s_waitcnt vmcnt(29)
	v_fmac_f32_e32 v12, v81, v112
	s_waitcnt vmcnt(28)
	v_fmac_f32_e32 v12, v82, v113
	ds_read_b128 v[110:113], v1 offset:160
	v_add_f32_e32 v11, v11, v12
	s_waitcnt vmcnt(26) lgkmcnt(1)
	v_mul_f32_e32 v12, v83, v115
	v_fmac_f32_e32 v12, v79, v114
	s_waitcnt vmcnt(25)
	v_fmac_f32_e32 v12, v77, v116
	s_waitcnt vmcnt(24)
	v_fmac_f32_e32 v12, v78, v117
	ds_read_b128 v[114:117], v1 offset:176
	v_add_f32_e32 v11, v11, v12
	s_waitcnt vmcnt(22) lgkmcnt(1)
	v_mul_f32_e32 v12, v92, v111
	v_fmac_f32_e32 v12, v88, v110
	s_waitcnt vmcnt(21)
	v_fmac_f32_e32 v12, v89, v112
	s_waitcnt vmcnt(20)
	v_fmac_f32_e32 v12, v90, v113
	ds_read_b128 v[110:113], v1 offset:192
	v_add_f32_e32 v11, v11, v12
	s_waitcnt vmcnt(18) lgkmcnt(1)
	v_mul_f32_e32 v12, v91, v115
	v_fmac_f32_e32 v12, v87, v114
	s_waitcnt vmcnt(17)
	v_fmac_f32_e32 v12, v85, v116
	s_waitcnt vmcnt(16)
	v_fmac_f32_e32 v12, v86, v117
	ds_read_b128 v[114:117], v1 offset:208
	v_add_f32_e32 v11, v11, v12
	s_waitcnt vmcnt(14) lgkmcnt(1)
	v_mul_f32_e32 v12, v100, v111
	v_fmac_f32_e32 v12, v96, v110
	s_waitcnt vmcnt(13)
	v_fmac_f32_e32 v12, v97, v112
	s_waitcnt vmcnt(12)
	v_fmac_f32_e32 v12, v98, v113
	ds_read_b128 v[110:113], v1 offset:224
	v_add_f32_e32 v11, v11, v12
	s_waitcnt vmcnt(10) lgkmcnt(1)
	v_mul_f32_e32 v12, v99, v115
	v_fmac_f32_e32 v12, v95, v114
	s_waitcnt vmcnt(9)
	v_fmac_f32_e32 v12, v93, v116
	s_waitcnt vmcnt(8)
	v_fmac_f32_e32 v12, v94, v117
	ds_read_b128 v[114:117], v1 offset:240
	v_add_f32_e32 v11, v11, v12
	s_waitcnt vmcnt(6) lgkmcnt(1)
	v_mul_f32_e32 v12, v108, v111
	v_fmac_f32_e32 v12, v104, v110
	s_waitcnt vmcnt(5)
	v_fmac_f32_e32 v12, v105, v112
	s_waitcnt vmcnt(4)
	v_fmac_f32_e32 v12, v106, v113
	v_add_f32_e32 v11, v11, v12
	s_waitcnt vmcnt(2) lgkmcnt(0)
	v_mul_f32_e32 v12, v107, v115
	v_fmac_f32_e32 v12, v102, v114
	s_waitcnt vmcnt(1)
	v_fmac_f32_e32 v12, v103, v116
	s_waitcnt vmcnt(0)
	v_fmac_f32_e32 v12, v101, v117
	v_add_f32_e32 v11, v11, v12
	v_mad_u64_u32 v[12:13], s[26:27], v14, s26, v[10:11]
	ds_write_b32 v12, v11 offset:36864
	ds_read_b128 v[110:113], v1 offset:4096
	ds_read_b128 v[114:117], v1 offset:4112
	ds_read_b128 v[118:121], v1 offset:4128
	ds_read_b128 v[122:125], v1 offset:4144
	s_movk_i32 s26, 0x120
	s_waitcnt lgkmcnt(3)
	v_mul_f32_e32 v11, v52, v111
	v_fmac_f32_e32 v11, v50, v110
	s_waitcnt lgkmcnt(2)
	v_mul_f32_e32 v13, v49, v115
	v_fmac_f32_e32 v11, v51, v112
	v_fmac_f32_e32 v13, v46, v114
	v_fmac_f32_e32 v11, v48, v113
	v_fmac_f32_e32 v13, v47, v116
	v_add_f32_e32 v11, 0, v11
	v_fmac_f32_e32 v13, v9, v117
	v_add_f32_e32 v11, v11, v13
	s_waitcnt lgkmcnt(1)
	v_mul_f32_e32 v13, v60, v119
	v_fmac_f32_e32 v13, v58, v118
	v_fmac_f32_e32 v13, v59, v120
	v_fmac_f32_e32 v13, v56, v121
	ds_read_b128 v[110:113], v1 offset:4160
	ds_read_b128 v[114:117], v1 offset:4176
	v_add_f32_e32 v11, v11, v13
	s_waitcnt lgkmcnt(2)
	v_mul_f32_e32 v13, v57, v123
	v_fmac_f32_e32 v13, v55, v122
	v_fmac_f32_e32 v13, v53, v124
	v_fmac_f32_e32 v13, v54, v125
	v_add_f32_e32 v11, v11, v13
	s_waitcnt lgkmcnt(1)
	v_mul_f32_e32 v13, v68, v111
	v_fmac_f32_e32 v13, v64, v110
	v_fmac_f32_e32 v13, v65, v112
	v_fmac_f32_e32 v13, v66, v113
	ds_read_b128 v[110:113], v1 offset:4192
	v_add_f32_e32 v11, v11, v13
	s_waitcnt lgkmcnt(1)
	v_mul_f32_e32 v13, v67, v115
	v_fmac_f32_e32 v13, v63, v114
	v_fmac_f32_e32 v13, v61, v116
	v_fmac_f32_e32 v13, v62, v117
	ds_read_b128 v[114:117], v1 offset:4208
	v_add_f32_e32 v11, v11, v13
	s_waitcnt lgkmcnt(1)
	v_mul_f32_e32 v13, v76, v111
	v_fmac_f32_e32 v13, v72, v110
	v_fmac_f32_e32 v13, v73, v112
	v_fmac_f32_e32 v13, v74, v113
	ds_read_b128 v[110:113], v1 offset:4224
	v_add_f32_e32 v11, v11, v13
	s_waitcnt lgkmcnt(1)
	v_mul_f32_e32 v13, v75, v115
	v_fmac_f32_e32 v13, v71, v114
	v_fmac_f32_e32 v13, v69, v116
	v_fmac_f32_e32 v13, v70, v117
	ds_read_b128 v[114:117], v1 offset:4240
	v_add_f32_e32 v11, v11, v13
	s_waitcnt lgkmcnt(1)
	v_mul_f32_e32 v13, v84, v111
	v_fmac_f32_e32 v13, v80, v110
	v_fmac_f32_e32 v13, v81, v112
	v_fmac_f32_e32 v13, v82, v113
	ds_read_b128 v[110:113], v1 offset:4256
	v_add_f32_e32 v11, v11, v13
	s_waitcnt lgkmcnt(1)
	v_mul_f32_e32 v13, v83, v115
	v_fmac_f32_e32 v13, v79, v114
	v_fmac_f32_e32 v13, v77, v116
	v_fmac_f32_e32 v13, v78, v117
	ds_read_b128 v[114:117], v1 offset:4272
	v_add_f32_e32 v11, v11, v13
	s_waitcnt lgkmcnt(1)
	v_mul_f32_e32 v13, v92, v111
	v_fmac_f32_e32 v13, v88, v110
	v_fmac_f32_e32 v13, v89, v112
	v_fmac_f32_e32 v13, v90, v113
	ds_read_b128 v[110:113], v1 offset:4288
	v_add_f32_e32 v11, v11, v13
	s_waitcnt lgkmcnt(1)
	v_mul_f32_e32 v13, v91, v115
	v_fmac_f32_e32 v13, v87, v114
	v_fmac_f32_e32 v13, v85, v116
	v_fmac_f32_e32 v13, v86, v117
	ds_read_b128 v[114:117], v1 offset:4304
	v_add_f32_e32 v11, v11, v13
	s_waitcnt lgkmcnt(1)
	v_mul_f32_e32 v13, v100, v111
	v_fmac_f32_e32 v13, v96, v110
	v_fmac_f32_e32 v13, v97, v112
	v_fmac_f32_e32 v13, v98, v113
	ds_read_b128 v[110:113], v1 offset:4320
	v_add_f32_e32 v11, v11, v13
	s_waitcnt lgkmcnt(1)
	v_mul_f32_e32 v13, v99, v115
	v_fmac_f32_e32 v13, v95, v114
	v_fmac_f32_e32 v13, v93, v116
	v_fmac_f32_e32 v13, v94, v117
	ds_read_b128 v[114:117], v1 offset:4336
	v_add_f32_e32 v11, v11, v13
	s_waitcnt lgkmcnt(1)
	v_mul_f32_e32 v13, v108, v111
	v_fmac_f32_e32 v13, v104, v110
	v_fmac_f32_e32 v13, v105, v112
	v_fmac_f32_e32 v13, v106, v113
	v_add_f32_e32 v11, v11, v13
	s_waitcnt lgkmcnt(0)
	v_mul_f32_e32 v13, v107, v115
	v_fmac_f32_e32 v13, v102, v114
	v_fmac_f32_e32 v13, v103, v116
	v_fmac_f32_e32 v13, v101, v117
	v_add_f32_e32 v11, v11, v13
	ds_write_b32 v12, v11 offset:36992
	ds_read_b128 v[110:113], v1 offset:8192
	ds_read_b128 v[114:117], v1 offset:8208
	ds_read_b128 v[118:121], v1 offset:8224
	ds_read_b128 v[122:125], v1 offset:8240
	v_cmp_gt_i32_e32 vcc, s26, v0
	s_waitcnt lgkmcnt(3)
	v_mul_f32_e32 v11, v52, v111
	v_fmac_f32_e32 v11, v50, v110
	s_waitcnt lgkmcnt(2)
	v_mul_f32_e32 v13, v49, v115
	v_fmac_f32_e32 v11, v51, v112
	v_fmac_f32_e32 v13, v46, v114
	v_fmac_f32_e32 v11, v48, v113
	v_fmac_f32_e32 v13, v47, v116
	v_add_f32_e32 v11, 0, v11
	v_fmac_f32_e32 v13, v9, v117
	v_add_f32_e32 v11, v11, v13
	s_waitcnt lgkmcnt(1)
	v_mul_f32_e32 v13, v60, v119
	v_fmac_f32_e32 v13, v58, v118
	v_fmac_f32_e32 v13, v59, v120
	v_fmac_f32_e32 v13, v56, v121
	ds_read_b128 v[110:113], v1 offset:8256
	ds_read_b128 v[114:117], v1 offset:8272
	v_add_f32_e32 v11, v11, v13
	s_waitcnt lgkmcnt(2)
	v_mul_f32_e32 v13, v57, v123
	v_fmac_f32_e32 v13, v55, v122
	v_fmac_f32_e32 v13, v53, v124
	v_fmac_f32_e32 v13, v54, v125
	v_add_f32_e32 v11, v11, v13
	s_waitcnt lgkmcnt(1)
	v_mul_f32_e32 v13, v68, v111
	v_fmac_f32_e32 v13, v64, v110
	v_fmac_f32_e32 v13, v65, v112
	v_fmac_f32_e32 v13, v66, v113
	ds_read_b128 v[110:113], v1 offset:8288
	v_add_f32_e32 v11, v11, v13
	s_waitcnt lgkmcnt(1)
	v_mul_f32_e32 v13, v67, v115
	v_fmac_f32_e32 v13, v63, v114
	v_fmac_f32_e32 v13, v61, v116
	v_fmac_f32_e32 v13, v62, v117
	ds_read_b128 v[114:117], v1 offset:8304
	v_add_f32_e32 v11, v11, v13
	s_waitcnt lgkmcnt(1)
	v_mul_f32_e32 v13, v76, v111
	v_fmac_f32_e32 v13, v72, v110
	v_fmac_f32_e32 v13, v73, v112
	v_fmac_f32_e32 v13, v74, v113
	ds_read_b128 v[110:113], v1 offset:8320
	v_add_f32_e32 v11, v11, v13
	s_waitcnt lgkmcnt(1)
	v_mul_f32_e32 v13, v75, v115
	v_fmac_f32_e32 v13, v71, v114
	v_fmac_f32_e32 v13, v69, v116
	v_fmac_f32_e32 v13, v70, v117
	ds_read_b128 v[114:117], v1 offset:8336
	v_add_f32_e32 v11, v11, v13
	s_waitcnt lgkmcnt(1)
	v_mul_f32_e32 v13, v84, v111
	v_fmac_f32_e32 v13, v80, v110
	v_fmac_f32_e32 v13, v81, v112
	v_fmac_f32_e32 v13, v82, v113
	ds_read_b128 v[110:113], v1 offset:8352
	v_add_f32_e32 v11, v11, v13
	s_waitcnt lgkmcnt(1)
	v_mul_f32_e32 v13, v83, v115
	v_fmac_f32_e32 v13, v79, v114
	v_fmac_f32_e32 v13, v77, v116
	v_fmac_f32_e32 v13, v78, v117
	ds_read_b128 v[114:117], v1 offset:8368
	v_add_f32_e32 v11, v11, v13
	s_waitcnt lgkmcnt(1)
	v_mul_f32_e32 v13, v92, v111
	v_fmac_f32_e32 v13, v88, v110
	v_fmac_f32_e32 v13, v89, v112
	v_fmac_f32_e32 v13, v90, v113
	ds_read_b128 v[110:113], v1 offset:8384
	v_add_f32_e32 v11, v11, v13
	s_waitcnt lgkmcnt(1)
	v_mul_f32_e32 v13, v91, v115
	v_fmac_f32_e32 v13, v87, v114
	v_fmac_f32_e32 v13, v85, v116
	v_fmac_f32_e32 v13, v86, v117
	ds_read_b128 v[114:117], v1 offset:8400
	v_add_f32_e32 v11, v11, v13
	s_waitcnt lgkmcnt(1)
	v_mul_f32_e32 v13, v100, v111
	v_fmac_f32_e32 v13, v96, v110
	v_fmac_f32_e32 v13, v97, v112
	v_fmac_f32_e32 v13, v98, v113
	ds_read_b128 v[110:113], v1 offset:8416
	v_add_f32_e32 v11, v11, v13
	s_waitcnt lgkmcnt(1)
	v_mul_f32_e32 v13, v99, v115
	v_fmac_f32_e32 v13, v95, v114
	v_fmac_f32_e32 v13, v93, v116
	v_fmac_f32_e32 v13, v94, v117
	ds_read_b128 v[114:117], v1 offset:8432
	v_add_f32_e32 v11, v11, v13
	s_waitcnt lgkmcnt(1)
	v_mul_f32_e32 v13, v108, v111
	v_fmac_f32_e32 v13, v104, v110
	v_fmac_f32_e32 v13, v105, v112
	v_fmac_f32_e32 v13, v106, v113
	v_add_f32_e32 v11, v11, v13
	s_waitcnt lgkmcnt(0)
	v_mul_f32_e32 v13, v107, v115
	v_fmac_f32_e32 v13, v102, v114
	v_fmac_f32_e32 v13, v103, v116
	v_fmac_f32_e32 v13, v101, v117
	v_add_f32_e32 v11, v11, v13
	ds_write_b32 v12, v11 offset:37120
	ds_read_b128 v[110:113], v1 offset:12288
	ds_read_b128 v[114:117], v1 offset:12304
	ds_read_b128 v[118:121], v1 offset:12320
	ds_read_b128 v[122:125], v1 offset:12336
	s_waitcnt lgkmcnt(3)
	v_mul_f32_e32 v11, v52, v111
	v_fmac_f32_e32 v11, v50, v110
	s_waitcnt lgkmcnt(2)
	v_mul_f32_e32 v13, v49, v115
	v_fmac_f32_e32 v11, v51, v112
	v_fmac_f32_e32 v13, v46, v114
	v_fmac_f32_e32 v11, v48, v113
	v_fmac_f32_e32 v13, v47, v116
	v_add_f32_e32 v11, 0, v11
	v_fmac_f32_e32 v13, v9, v117
	v_add_f32_e32 v11, v11, v13
	s_waitcnt lgkmcnt(1)
	v_mul_f32_e32 v13, v60, v119
	v_fmac_f32_e32 v13, v58, v118
	v_fmac_f32_e32 v13, v59, v120
	v_fmac_f32_e32 v13, v56, v121
	ds_read_b128 v[110:113], v1 offset:12352
	ds_read_b128 v[114:117], v1 offset:12368
	v_add_f32_e32 v11, v11, v13
	s_waitcnt lgkmcnt(2)
	v_mul_f32_e32 v13, v57, v123
	v_fmac_f32_e32 v13, v55, v122
	v_fmac_f32_e32 v13, v53, v124
	v_fmac_f32_e32 v13, v54, v125
	v_add_f32_e32 v11, v11, v13
	s_waitcnt lgkmcnt(1)
	v_mul_f32_e32 v13, v68, v111
	v_fmac_f32_e32 v13, v64, v110
	v_fmac_f32_e32 v13, v65, v112
	v_fmac_f32_e32 v13, v66, v113
	ds_read_b128 v[110:113], v1 offset:12384
	v_add_f32_e32 v11, v11, v13
	s_waitcnt lgkmcnt(1)
	v_mul_f32_e32 v13, v67, v115
	v_fmac_f32_e32 v13, v63, v114
	v_fmac_f32_e32 v13, v61, v116
	v_fmac_f32_e32 v13, v62, v117
	ds_read_b128 v[114:117], v1 offset:12400
	v_add_f32_e32 v11, v11, v13
	s_waitcnt lgkmcnt(1)
	v_mul_f32_e32 v13, v76, v111
	v_fmac_f32_e32 v13, v72, v110
	v_fmac_f32_e32 v13, v73, v112
	v_fmac_f32_e32 v13, v74, v113
	ds_read_b128 v[110:113], v1 offset:12416
	v_add_f32_e32 v11, v11, v13
	s_waitcnt lgkmcnt(1)
	v_mul_f32_e32 v13, v75, v115
	v_fmac_f32_e32 v13, v71, v114
	v_fmac_f32_e32 v13, v69, v116
	v_fmac_f32_e32 v13, v70, v117
	ds_read_b128 v[114:117], v1 offset:12432
	v_add_f32_e32 v11, v11, v13
	s_waitcnt lgkmcnt(1)
	v_mul_f32_e32 v13, v84, v111
	v_fmac_f32_e32 v13, v80, v110
	v_fmac_f32_e32 v13, v81, v112
	v_fmac_f32_e32 v13, v82, v113
	ds_read_b128 v[110:113], v1 offset:12448
	v_add_f32_e32 v11, v11, v13
	s_waitcnt lgkmcnt(1)
	v_mul_f32_e32 v13, v83, v115
	v_fmac_f32_e32 v13, v79, v114
	v_fmac_f32_e32 v13, v77, v116
	v_fmac_f32_e32 v13, v78, v117
	ds_read_b128 v[114:117], v1 offset:12464
	v_add_f32_e32 v11, v11, v13
	s_waitcnt lgkmcnt(1)
	v_mul_f32_e32 v13, v92, v111
	v_fmac_f32_e32 v13, v88, v110
	v_fmac_f32_e32 v13, v89, v112
	v_fmac_f32_e32 v13, v90, v113
	ds_read_b128 v[110:113], v1 offset:12480
	v_add_f32_e32 v11, v11, v13
	s_waitcnt lgkmcnt(1)
	v_mul_f32_e32 v13, v91, v115
	v_fmac_f32_e32 v13, v87, v114
	v_fmac_f32_e32 v13, v85, v116
	v_fmac_f32_e32 v13, v86, v117
	ds_read_b128 v[114:117], v1 offset:12496
	v_add_f32_e32 v11, v11, v13
	s_waitcnt lgkmcnt(1)
	v_mul_f32_e32 v13, v100, v111
	v_fmac_f32_e32 v13, v96, v110
	v_fmac_f32_e32 v13, v97, v112
	v_fmac_f32_e32 v13, v98, v113
	ds_read_b128 v[110:113], v1 offset:12512
	v_add_f32_e32 v11, v11, v13
	s_waitcnt lgkmcnt(1)
	v_mul_f32_e32 v13, v99, v115
	v_fmac_f32_e32 v13, v95, v114
	v_fmac_f32_e32 v13, v93, v116
	v_fmac_f32_e32 v13, v94, v117
	ds_read_b128 v[114:117], v1 offset:12528
	v_add_f32_e32 v11, v11, v13
	s_waitcnt lgkmcnt(1)
	v_mul_f32_e32 v13, v108, v111
	v_fmac_f32_e32 v13, v104, v110
	v_fmac_f32_e32 v13, v105, v112
	v_fmac_f32_e32 v13, v106, v113
	v_add_f32_e32 v11, v11, v13
	s_waitcnt lgkmcnt(0)
	v_mul_f32_e32 v13, v107, v115
	v_fmac_f32_e32 v13, v102, v114
	v_fmac_f32_e32 v13, v103, v116
	v_fmac_f32_e32 v13, v101, v117
	v_add_f32_e32 v11, v11, v13
	ds_write_b32 v12, v11 offset:37248
	ds_read_b128 v[110:113], v1 offset:16384
	ds_read_b128 v[114:117], v1 offset:16400
	ds_read_b128 v[118:121], v1 offset:16416
	ds_read_b128 v[122:125], v1 offset:16432
	s_waitcnt lgkmcnt(3)
	v_mul_f32_e32 v11, v52, v111
	v_fmac_f32_e32 v11, v50, v110
	s_waitcnt lgkmcnt(2)
	v_mul_f32_e32 v13, v49, v115
	v_fmac_f32_e32 v11, v51, v112
	v_fmac_f32_e32 v13, v46, v114
	v_fmac_f32_e32 v11, v48, v113
	v_fmac_f32_e32 v13, v47, v116
	v_add_f32_e32 v11, 0, v11
	v_fmac_f32_e32 v13, v9, v117
	v_add_f32_e32 v11, v11, v13
	s_waitcnt lgkmcnt(1)
	v_mul_f32_e32 v13, v60, v119
	v_fmac_f32_e32 v13, v58, v118
	v_fmac_f32_e32 v13, v59, v120
	v_fmac_f32_e32 v13, v56, v121
	ds_read_b128 v[110:113], v1 offset:16448
	ds_read_b128 v[114:117], v1 offset:16464
	v_add_f32_e32 v11, v11, v13
	s_waitcnt lgkmcnt(2)
	v_mul_f32_e32 v13, v57, v123
	v_fmac_f32_e32 v13, v55, v122
	v_fmac_f32_e32 v13, v53, v124
	v_fmac_f32_e32 v13, v54, v125
	v_add_f32_e32 v11, v11, v13
	s_waitcnt lgkmcnt(1)
	v_mul_f32_e32 v13, v68, v111
	v_fmac_f32_e32 v13, v64, v110
	v_fmac_f32_e32 v13, v65, v112
	v_fmac_f32_e32 v13, v66, v113
	ds_read_b128 v[110:113], v1 offset:16480
	v_add_f32_e32 v11, v11, v13
	s_waitcnt lgkmcnt(1)
	v_mul_f32_e32 v13, v67, v115
	v_fmac_f32_e32 v13, v63, v114
	v_fmac_f32_e32 v13, v61, v116
	v_fmac_f32_e32 v13, v62, v117
	ds_read_b128 v[114:117], v1 offset:16496
	v_add_f32_e32 v11, v11, v13
	s_waitcnt lgkmcnt(1)
	v_mul_f32_e32 v13, v76, v111
	v_fmac_f32_e32 v13, v72, v110
	v_fmac_f32_e32 v13, v73, v112
	v_fmac_f32_e32 v13, v74, v113
	ds_read_b128 v[110:113], v1 offset:16512
	v_add_f32_e32 v11, v11, v13
	s_waitcnt lgkmcnt(1)
	v_mul_f32_e32 v13, v75, v115
	v_fmac_f32_e32 v13, v71, v114
	v_fmac_f32_e32 v13, v69, v116
	v_fmac_f32_e32 v13, v70, v117
	ds_read_b128 v[114:117], v1 offset:16528
	v_add_f32_e32 v11, v11, v13
	s_waitcnt lgkmcnt(1)
	v_mul_f32_e32 v13, v84, v111
	v_fmac_f32_e32 v13, v80, v110
	v_fmac_f32_e32 v13, v81, v112
	v_fmac_f32_e32 v13, v82, v113
	ds_read_b128 v[110:113], v1 offset:16544
	v_add_f32_e32 v11, v11, v13
	s_waitcnt lgkmcnt(1)
	v_mul_f32_e32 v13, v83, v115
	v_fmac_f32_e32 v13, v79, v114
	v_fmac_f32_e32 v13, v77, v116
	v_fmac_f32_e32 v13, v78, v117
	ds_read_b128 v[114:117], v1 offset:16560
	v_add_f32_e32 v11, v11, v13
	s_waitcnt lgkmcnt(1)
	v_mul_f32_e32 v13, v92, v111
	v_fmac_f32_e32 v13, v88, v110
	v_fmac_f32_e32 v13, v89, v112
	v_fmac_f32_e32 v13, v90, v113
	ds_read_b128 v[110:113], v1 offset:16576
	v_add_f32_e32 v11, v11, v13
	s_waitcnt lgkmcnt(1)
	v_mul_f32_e32 v13, v91, v115
	v_fmac_f32_e32 v13, v87, v114
	v_fmac_f32_e32 v13, v85, v116
	v_fmac_f32_e32 v13, v86, v117
	ds_read_b128 v[114:117], v1 offset:16592
	v_add_f32_e32 v11, v11, v13
	s_waitcnt lgkmcnt(1)
	v_mul_f32_e32 v13, v100, v111
	v_fmac_f32_e32 v13, v96, v110
	v_fmac_f32_e32 v13, v97, v112
	v_fmac_f32_e32 v13, v98, v113
	ds_read_b128 v[110:113], v1 offset:16608
	v_add_f32_e32 v11, v11, v13
	s_waitcnt lgkmcnt(1)
	v_mul_f32_e32 v13, v99, v115
	v_fmac_f32_e32 v13, v95, v114
	v_fmac_f32_e32 v13, v93, v116
	v_fmac_f32_e32 v13, v94, v117
	ds_read_b128 v[114:117], v1 offset:16624
	v_add_f32_e32 v11, v11, v13
	s_waitcnt lgkmcnt(1)
	v_mul_f32_e32 v13, v108, v111
	v_fmac_f32_e32 v13, v104, v110
	v_fmac_f32_e32 v13, v105, v112
	v_fmac_f32_e32 v13, v106, v113
	v_add_f32_e32 v11, v11, v13
	s_waitcnt lgkmcnt(0)
	v_mul_f32_e32 v13, v107, v115
	v_fmac_f32_e32 v13, v102, v114
	v_fmac_f32_e32 v13, v103, v116
	v_fmac_f32_e32 v13, v101, v117
	v_add_f32_e32 v11, v11, v13
	ds_write_b32 v12, v11 offset:37376
	ds_read_b128 v[110:113], v1 offset:20480
	ds_read_b128 v[114:117], v1 offset:20496
	ds_read_b128 v[118:121], v1 offset:20512
	ds_read_b128 v[122:125], v1 offset:20528
	s_waitcnt lgkmcnt(3)
	v_mul_f32_e32 v11, v52, v111
	v_fmac_f32_e32 v11, v50, v110
	s_waitcnt lgkmcnt(2)
	v_mul_f32_e32 v13, v49, v115
	v_fmac_f32_e32 v11, v51, v112
	v_fmac_f32_e32 v13, v46, v114
	v_fmac_f32_e32 v11, v48, v113
	v_fmac_f32_e32 v13, v47, v116
	v_add_f32_e32 v11, 0, v11
	v_fmac_f32_e32 v13, v9, v117
	v_add_f32_e32 v11, v11, v13
	s_waitcnt lgkmcnt(1)
	v_mul_f32_e32 v13, v60, v119
	v_fmac_f32_e32 v13, v58, v118
	v_fmac_f32_e32 v13, v59, v120
	v_fmac_f32_e32 v13, v56, v121
	ds_read_b128 v[110:113], v1 offset:20544
	ds_read_b128 v[114:117], v1 offset:20560
	v_add_f32_e32 v11, v11, v13
	s_waitcnt lgkmcnt(2)
	v_mul_f32_e32 v13, v57, v123
	v_fmac_f32_e32 v13, v55, v122
	v_fmac_f32_e32 v13, v53, v124
	v_fmac_f32_e32 v13, v54, v125
	v_add_f32_e32 v11, v11, v13
	s_waitcnt lgkmcnt(1)
	v_mul_f32_e32 v13, v68, v111
	v_fmac_f32_e32 v13, v64, v110
	v_fmac_f32_e32 v13, v65, v112
	v_fmac_f32_e32 v13, v66, v113
	ds_read_b128 v[110:113], v1 offset:20576
	v_add_f32_e32 v11, v11, v13
	s_waitcnt lgkmcnt(1)
	v_mul_f32_e32 v13, v67, v115
	v_fmac_f32_e32 v13, v63, v114
	v_fmac_f32_e32 v13, v61, v116
	v_fmac_f32_e32 v13, v62, v117
	ds_read_b128 v[114:117], v1 offset:20592
	v_add_f32_e32 v11, v11, v13
	s_waitcnt lgkmcnt(1)
	v_mul_f32_e32 v13, v76, v111
	v_fmac_f32_e32 v13, v72, v110
	v_fmac_f32_e32 v13, v73, v112
	v_fmac_f32_e32 v13, v74, v113
	ds_read_b128 v[110:113], v1 offset:20608
	v_add_f32_e32 v11, v11, v13
	s_waitcnt lgkmcnt(1)
	v_mul_f32_e32 v13, v75, v115
	v_fmac_f32_e32 v13, v71, v114
	v_fmac_f32_e32 v13, v69, v116
	v_fmac_f32_e32 v13, v70, v117
	ds_read_b128 v[114:117], v1 offset:20624
	v_add_f32_e32 v11, v11, v13
	s_waitcnt lgkmcnt(1)
	v_mul_f32_e32 v13, v84, v111
	v_fmac_f32_e32 v13, v80, v110
	v_fmac_f32_e32 v13, v81, v112
	v_fmac_f32_e32 v13, v82, v113
	ds_read_b128 v[110:113], v1 offset:20640
	v_add_f32_e32 v11, v11, v13
	s_waitcnt lgkmcnt(1)
	v_mul_f32_e32 v13, v83, v115
	v_fmac_f32_e32 v13, v79, v114
	v_fmac_f32_e32 v13, v77, v116
	v_fmac_f32_e32 v13, v78, v117
	ds_read_b128 v[114:117], v1 offset:20656
	v_add_f32_e32 v11, v11, v13
	s_waitcnt lgkmcnt(1)
	v_mul_f32_e32 v13, v92, v111
	v_fmac_f32_e32 v13, v88, v110
	v_fmac_f32_e32 v13, v89, v112
	v_fmac_f32_e32 v13, v90, v113
	ds_read_b128 v[110:113], v1 offset:20672
	v_add_f32_e32 v11, v11, v13
	s_waitcnt lgkmcnt(1)
	v_mul_f32_e32 v13, v91, v115
	v_fmac_f32_e32 v13, v87, v114
	v_fmac_f32_e32 v13, v85, v116
	v_fmac_f32_e32 v13, v86, v117
	ds_read_b128 v[114:117], v1 offset:20688
	v_add_f32_e32 v11, v11, v13
	s_waitcnt lgkmcnt(1)
	v_mul_f32_e32 v13, v100, v111
	v_fmac_f32_e32 v13, v96, v110
	v_fmac_f32_e32 v13, v97, v112
	v_fmac_f32_e32 v13, v98, v113
	ds_read_b128 v[110:113], v1 offset:20704
	v_add_f32_e32 v11, v11, v13
	s_waitcnt lgkmcnt(1)
	v_mul_f32_e32 v13, v99, v115
	v_fmac_f32_e32 v13, v95, v114
	v_fmac_f32_e32 v13, v93, v116
	v_fmac_f32_e32 v13, v94, v117
	ds_read_b128 v[114:117], v1 offset:20720
	v_add_f32_e32 v11, v11, v13
	s_waitcnt lgkmcnt(1)
	v_mul_f32_e32 v13, v108, v111
	v_fmac_f32_e32 v13, v104, v110
	v_fmac_f32_e32 v13, v105, v112
	v_fmac_f32_e32 v13, v106, v113
	v_add_f32_e32 v11, v11, v13
	s_waitcnt lgkmcnt(0)
	v_mul_f32_e32 v13, v107, v115
	v_fmac_f32_e32 v13, v102, v114
	v_fmac_f32_e32 v13, v103, v116
	v_fmac_f32_e32 v13, v101, v117
	v_add_f32_e32 v11, v11, v13
	ds_write_b32 v12, v11 offset:37504
	ds_read_b128 v[110:113], v1 offset:24576
	ds_read_b128 v[114:117], v1 offset:24592
	ds_read_b128 v[118:121], v1 offset:24608
	ds_read_b128 v[122:125], v1 offset:24624
	s_waitcnt lgkmcnt(3)
	v_mul_f32_e32 v11, v52, v111
	v_fmac_f32_e32 v11, v50, v110
	s_waitcnt lgkmcnt(2)
	v_mul_f32_e32 v13, v49, v115
	v_fmac_f32_e32 v11, v51, v112
	v_fmac_f32_e32 v13, v46, v114
	v_fmac_f32_e32 v11, v48, v113
	v_fmac_f32_e32 v13, v47, v116
	v_add_f32_e32 v11, 0, v11
	v_fmac_f32_e32 v13, v9, v117
	v_add_f32_e32 v11, v11, v13
	s_waitcnt lgkmcnt(1)
	v_mul_f32_e32 v13, v60, v119
	v_fmac_f32_e32 v13, v58, v118
	v_fmac_f32_e32 v13, v59, v120
	v_fmac_f32_e32 v13, v56, v121
	ds_read_b128 v[110:113], v1 offset:24640
	ds_read_b128 v[114:117], v1 offset:24656
	v_add_f32_e32 v11, v11, v13
	s_waitcnt lgkmcnt(2)
	v_mul_f32_e32 v13, v57, v123
	v_fmac_f32_e32 v13, v55, v122
	v_fmac_f32_e32 v13, v53, v124
	v_fmac_f32_e32 v13, v54, v125
	v_add_f32_e32 v11, v11, v13
	s_waitcnt lgkmcnt(1)
	v_mul_f32_e32 v13, v68, v111
	v_fmac_f32_e32 v13, v64, v110
	v_fmac_f32_e32 v13, v65, v112
	v_fmac_f32_e32 v13, v66, v113
	ds_read_b128 v[110:113], v1 offset:24672
	v_add_f32_e32 v11, v11, v13
	s_waitcnt lgkmcnt(1)
	v_mul_f32_e32 v13, v67, v115
	v_fmac_f32_e32 v13, v63, v114
	v_fmac_f32_e32 v13, v61, v116
	v_fmac_f32_e32 v13, v62, v117
	ds_read_b128 v[114:117], v1 offset:24688
	v_add_f32_e32 v11, v11, v13
	s_waitcnt lgkmcnt(1)
	v_mul_f32_e32 v13, v76, v111
	v_fmac_f32_e32 v13, v72, v110
	v_fmac_f32_e32 v13, v73, v112
	v_fmac_f32_e32 v13, v74, v113
	ds_read_b128 v[110:113], v1 offset:24704
	v_add_f32_e32 v11, v11, v13
	s_waitcnt lgkmcnt(1)
	v_mul_f32_e32 v13, v75, v115
	v_fmac_f32_e32 v13, v71, v114
	v_fmac_f32_e32 v13, v69, v116
	v_fmac_f32_e32 v13, v70, v117
	ds_read_b128 v[114:117], v1 offset:24720
	v_add_f32_e32 v11, v11, v13
	s_waitcnt lgkmcnt(1)
	v_mul_f32_e32 v13, v84, v111
	v_fmac_f32_e32 v13, v80, v110
	v_fmac_f32_e32 v13, v81, v112
	v_fmac_f32_e32 v13, v82, v113
	ds_read_b128 v[110:113], v1 offset:24736
	v_add_f32_e32 v11, v11, v13
	s_waitcnt lgkmcnt(1)
	v_mul_f32_e32 v13, v83, v115
	v_fmac_f32_e32 v13, v79, v114
	v_fmac_f32_e32 v13, v77, v116
	v_fmac_f32_e32 v13, v78, v117
	ds_read_b128 v[114:117], v1 offset:24752
	v_add_f32_e32 v11, v11, v13
	s_waitcnt lgkmcnt(1)
	v_mul_f32_e32 v13, v92, v111
	v_fmac_f32_e32 v13, v88, v110
	v_fmac_f32_e32 v13, v89, v112
	v_fmac_f32_e32 v13, v90, v113
	ds_read_b128 v[110:113], v1 offset:24768
	v_add_f32_e32 v11, v11, v13
	s_waitcnt lgkmcnt(1)
	v_mul_f32_e32 v13, v91, v115
	v_fmac_f32_e32 v13, v87, v114
	v_fmac_f32_e32 v13, v85, v116
	v_fmac_f32_e32 v13, v86, v117
	ds_read_b128 v[114:117], v1 offset:24784
	v_add_f32_e32 v11, v11, v13
	s_waitcnt lgkmcnt(1)
	v_mul_f32_e32 v13, v100, v111
	v_fmac_f32_e32 v13, v96, v110
	v_fmac_f32_e32 v13, v97, v112
	v_fmac_f32_e32 v13, v98, v113
	ds_read_b128 v[110:113], v1 offset:24800
	v_add_f32_e32 v11, v11, v13
	s_waitcnt lgkmcnt(1)
	v_mul_f32_e32 v13, v99, v115
	v_fmac_f32_e32 v13, v95, v114
	v_fmac_f32_e32 v13, v93, v116
	v_fmac_f32_e32 v13, v94, v117
	ds_read_b128 v[114:117], v1 offset:24816
	v_add_f32_e32 v11, v11, v13
	s_waitcnt lgkmcnt(1)
	v_mul_f32_e32 v13, v108, v111
	v_fmac_f32_e32 v13, v104, v110
	v_fmac_f32_e32 v13, v105, v112
	v_fmac_f32_e32 v13, v106, v113
	v_add_f32_e32 v11, v11, v13
	s_waitcnt lgkmcnt(0)
	v_mul_f32_e32 v13, v107, v115
	v_fmac_f32_e32 v13, v102, v114
	v_fmac_f32_e32 v13, v103, v116
	v_fmac_f32_e32 v13, v101, v117
	v_add_f32_e32 v11, v11, v13
	ds_write_b32 v12, v11 offset:37632
	ds_read_b128 v[110:113], v1 offset:28672
	ds_read_b128 v[114:117], v1 offset:28688
	ds_read_b128 v[118:121], v1 offset:28704
	ds_read_b128 v[122:125], v1 offset:28720
	s_waitcnt lgkmcnt(3)
	v_mul_f32_e32 v11, v52, v111
	v_fmac_f32_e32 v11, v50, v110
	s_waitcnt lgkmcnt(2)
	v_mul_f32_e32 v13, v49, v115
	v_fmac_f32_e32 v11, v51, v112
	v_fmac_f32_e32 v13, v46, v114
	v_fmac_f32_e32 v11, v48, v113
	v_fmac_f32_e32 v13, v47, v116
	v_add_f32_e32 v11, 0, v11
	v_fmac_f32_e32 v13, v9, v117
	v_add_f32_e32 v11, v11, v13
	s_waitcnt lgkmcnt(1)
	v_mul_f32_e32 v13, v60, v119
	v_fmac_f32_e32 v13, v58, v118
	v_fmac_f32_e32 v13, v59, v120
	v_fmac_f32_e32 v13, v56, v121
	ds_read_b128 v[110:113], v1 offset:28736
	ds_read_b128 v[114:117], v1 offset:28752
	v_add_f32_e32 v11, v11, v13
	s_waitcnt lgkmcnt(2)
	v_mul_f32_e32 v13, v57, v123
	v_fmac_f32_e32 v13, v55, v122
	v_fmac_f32_e32 v13, v53, v124
	v_fmac_f32_e32 v13, v54, v125
	v_add_f32_e32 v11, v11, v13
	s_waitcnt lgkmcnt(1)
	v_mul_f32_e32 v13, v68, v111
	v_fmac_f32_e32 v13, v64, v110
	v_fmac_f32_e32 v13, v65, v112
	v_fmac_f32_e32 v13, v66, v113
	ds_read_b128 v[110:113], v1 offset:28768
	v_add_f32_e32 v11, v11, v13
	s_waitcnt lgkmcnt(1)
	v_mul_f32_e32 v13, v67, v115
	v_fmac_f32_e32 v13, v63, v114
	v_fmac_f32_e32 v13, v61, v116
	v_fmac_f32_e32 v13, v62, v117
	ds_read_b128 v[114:117], v1 offset:28784
	v_add_f32_e32 v11, v11, v13
	s_waitcnt lgkmcnt(1)
	v_mul_f32_e32 v13, v76, v111
	v_fmac_f32_e32 v13, v72, v110
	v_fmac_f32_e32 v13, v73, v112
	v_fmac_f32_e32 v13, v74, v113
	ds_read_b128 v[110:113], v1 offset:28800
	v_add_f32_e32 v11, v11, v13
	s_waitcnt lgkmcnt(1)
	v_mul_f32_e32 v13, v75, v115
	v_fmac_f32_e32 v13, v71, v114
	v_fmac_f32_e32 v13, v69, v116
	v_fmac_f32_e32 v13, v70, v117
	ds_read_b128 v[114:117], v1 offset:28816
	v_add_f32_e32 v11, v11, v13
	s_waitcnt lgkmcnt(1)
	v_mul_f32_e32 v13, v84, v111
	v_fmac_f32_e32 v13, v80, v110
	v_fmac_f32_e32 v13, v81, v112
	v_fmac_f32_e32 v13, v82, v113
	ds_read_b128 v[110:113], v1 offset:28832
	v_add_f32_e32 v11, v11, v13
	s_waitcnt lgkmcnt(1)
	v_mul_f32_e32 v13, v83, v115
	v_fmac_f32_e32 v13, v79, v114
	v_fmac_f32_e32 v13, v77, v116
	v_fmac_f32_e32 v13, v78, v117
	ds_read_b128 v[114:117], v1 offset:28848
	v_add_f32_e32 v11, v11, v13
	s_waitcnt lgkmcnt(1)
	v_mul_f32_e32 v13, v92, v111
	v_fmac_f32_e32 v13, v88, v110
	v_fmac_f32_e32 v13, v89, v112
	v_fmac_f32_e32 v13, v90, v113
	ds_read_b128 v[110:113], v1 offset:28864
	v_add_f32_e32 v11, v11, v13
	s_waitcnt lgkmcnt(1)
	v_mul_f32_e32 v13, v91, v115
	v_fmac_f32_e32 v13, v87, v114
	v_fmac_f32_e32 v13, v85, v116
	v_fmac_f32_e32 v13, v86, v117
	ds_read_b128 v[114:117], v1 offset:28880
	v_add_f32_e32 v11, v11, v13
	s_waitcnt lgkmcnt(1)
	v_mul_f32_e32 v13, v100, v111
	v_fmac_f32_e32 v13, v96, v110
	v_fmac_f32_e32 v13, v97, v112
	v_fmac_f32_e32 v13, v98, v113
	ds_read_b128 v[110:113], v1 offset:28896
	v_add_f32_e32 v11, v11, v13
	s_waitcnt lgkmcnt(1)
	v_mul_f32_e32 v13, v99, v115
	v_fmac_f32_e32 v13, v95, v114
	v_fmac_f32_e32 v13, v93, v116
	v_fmac_f32_e32 v13, v94, v117
	ds_read_b128 v[114:117], v1 offset:28912
	v_add_f32_e32 v11, v11, v13
	s_waitcnt lgkmcnt(1)
	v_mul_f32_e32 v13, v108, v111
	v_fmac_f32_e32 v13, v104, v110
	v_fmac_f32_e32 v13, v105, v112
	v_fmac_f32_e32 v13, v106, v113
	v_add_f32_e32 v11, v11, v13
	s_waitcnt lgkmcnt(0)
	v_mul_f32_e32 v13, v107, v115
	v_fmac_f32_e32 v13, v102, v114
	v_fmac_f32_e32 v13, v103, v116
	v_fmac_f32_e32 v13, v101, v117
	v_add_f32_e32 v11, v11, v13
	ds_write_b32 v12, v11 offset:37760
	ds_read_b128 v[110:113], v1 offset:32768
	ds_read_b128 v[114:117], v1 offset:32784
	ds_read_b128 v[118:121], v1 offset:32800
	ds_read_b128 v[122:125], v1 offset:32816
	s_waitcnt lgkmcnt(3)
	v_mul_f32_e32 v11, v52, v111
	v_fmac_f32_e32 v11, v50, v110
	s_waitcnt lgkmcnt(2)
	v_mul_f32_e32 v13, v49, v115
	v_fmac_f32_e32 v11, v51, v112
	v_fmac_f32_e32 v13, v46, v114
	v_fmac_f32_e32 v11, v48, v113
	v_fmac_f32_e32 v13, v47, v116
	v_add_f32_e32 v11, 0, v11
	v_fmac_f32_e32 v13, v9, v117
	v_add_f32_e32 v9, v11, v13
	s_waitcnt lgkmcnt(1)
	v_mul_f32_e32 v11, v60, v119
	v_fmac_f32_e32 v11, v58, v118
	v_fmac_f32_e32 v11, v59, v120
	v_fmac_f32_e32 v11, v56, v121
	ds_read_b128 v[46:49], v1 offset:32832
	v_add_f32_e32 v9, v9, v11
	s_waitcnt lgkmcnt(1)
	v_mul_f32_e32 v11, v57, v123
	v_fmac_f32_e32 v11, v55, v122
	v_fmac_f32_e32 v11, v53, v124
	v_fmac_f32_e32 v11, v54, v125
	ds_read_b128 v[50:53], v1 offset:32848
	v_add_f32_e32 v9, v9, v11
	s_waitcnt lgkmcnt(1)
	v_mul_f32_e32 v11, v68, v47
	v_fmac_f32_e32 v11, v64, v46
	v_fmac_f32_e32 v11, v65, v48
	v_fmac_f32_e32 v11, v66, v49
	ds_read_b128 v[46:49], v1 offset:32864
	v_add_f32_e32 v9, v9, v11
	s_waitcnt lgkmcnt(1)
	v_mul_f32_e32 v11, v67, v51
	v_fmac_f32_e32 v11, v63, v50
	v_fmac_f32_e32 v11, v61, v52
	v_fmac_f32_e32 v11, v62, v53
	ds_read_b128 v[50:53], v1 offset:32880
	v_add_f32_e32 v9, v9, v11
	s_waitcnt lgkmcnt(1)
	v_mul_f32_e32 v11, v76, v47
	v_fmac_f32_e32 v11, v72, v46
	v_fmac_f32_e32 v11, v73, v48
	v_fmac_f32_e32 v11, v74, v49
	ds_read_b128 v[46:49], v1 offset:32896
	v_add_f32_e32 v9, v9, v11
	s_waitcnt lgkmcnt(1)
	v_mul_f32_e32 v11, v75, v51
	v_fmac_f32_e32 v11, v71, v50
	v_fmac_f32_e32 v11, v69, v52
	v_fmac_f32_e32 v11, v70, v53
	ds_read_b128 v[50:53], v1 offset:32912
	v_add_f32_e32 v9, v9, v11
	s_waitcnt lgkmcnt(1)
	v_mul_f32_e32 v11, v84, v47
	v_fmac_f32_e32 v11, v80, v46
	v_fmac_f32_e32 v11, v81, v48
	v_fmac_f32_e32 v11, v82, v49
	ds_read_b128 v[46:49], v1 offset:32928
	v_add_f32_e32 v9, v9, v11
	s_waitcnt lgkmcnt(1)
	v_mul_f32_e32 v11, v83, v51
	v_fmac_f32_e32 v11, v79, v50
	v_fmac_f32_e32 v11, v77, v52
	v_fmac_f32_e32 v11, v78, v53
	ds_read_b128 v[50:53], v1 offset:32944
	v_add_f32_e32 v9, v9, v11
	s_waitcnt lgkmcnt(1)
	v_mul_f32_e32 v11, v92, v47
	v_fmac_f32_e32 v11, v88, v46
	v_fmac_f32_e32 v11, v89, v48
	v_fmac_f32_e32 v11, v90, v49
	ds_read_b128 v[46:49], v1 offset:32960
	v_add_f32_e32 v9, v9, v11
	s_waitcnt lgkmcnt(1)
	v_mul_f32_e32 v11, v91, v51
	v_fmac_f32_e32 v11, v87, v50
	v_fmac_f32_e32 v11, v85, v52
	v_fmac_f32_e32 v11, v86, v53
	ds_read_b128 v[50:53], v1 offset:32976
	v_add_f32_e32 v9, v9, v11
	s_waitcnt lgkmcnt(1)
	v_mul_f32_e32 v11, v100, v47
	v_fmac_f32_e32 v11, v96, v46
	v_fmac_f32_e32 v11, v97, v48
	v_fmac_f32_e32 v11, v98, v49
	ds_read_b128 v[46:49], v1 offset:32992
	v_add_f32_e32 v9, v9, v11
	s_waitcnt lgkmcnt(1)
	v_mul_f32_e32 v11, v99, v51
	v_fmac_f32_e32 v11, v95, v50
	v_fmac_f32_e32 v11, v93, v52
	v_fmac_f32_e32 v11, v94, v53
	ds_read_b128 v[50:53], v1 offset:33008
	s_waitcnt lgkmcnt(1)
	v_mul_f32_e32 v1, v108, v47
	v_fmac_f32_e32 v1, v104, v46
	v_fmac_f32_e32 v1, v105, v48
	v_add_f32_e32 v9, v9, v11
	v_fmac_f32_e32 v1, v106, v49
	v_add_f32_e32 v1, v9, v1
	s_waitcnt lgkmcnt(0)
	v_mul_f32_e32 v9, v107, v51
	v_fmac_f32_e32 v9, v102, v50
	v_fmac_f32_e32 v9, v103, v52
	v_fmac_f32_e32 v9, v101, v53
	v_add_f32_e32 v1, v1, v9
	ds_write_b32 v12, v1 offset:37888
	s_waitcnt lgkmcnt(0)
	s_barrier
	s_and_saveexec_b64 s[34:35], vcc
	s_cbranch_execz .LBB0_60
	v_mov_b32_e32 v12, s12
	v_mov_b32_e32 v13, s13
	v_ashrrev_i32_e32 v9, 31, v8
	v_lshl_add_u64 v[8:9], v[8:9], 2, v[12:13]
	v_mov_b32_e32 v1, v144
	v_lshl_add_u32 v8, v14, 7, v10
	v_mad_i32_i24 v9, v15, 9, v14
	ds_read_b32 v10, v8 offset:36864
	ds_read_b32 v11, v8 offset:38016
	ds_read_b32 v12, v8 offset:39168
	ds_read_b32 v13, v8 offset:40320
	ds_read_b32 v14, v8 offset:41472
	ds_read_b32 v15, v8 offset:42624
	ds_read_b32 v46, v8 offset:43776
	ds_read_b32 v47, v8 offset:44928
	ds_read_b32 v48, v8 offset:46080
	ds_read_b32 v49, v8 offset:47232
	ds_read_b32 v50, v8 offset:48384
	ds_read_b32 v51, v8 offset:49536
	ds_read_b32 v52, v8 offset:50688
	ds_read_b32 v53, v8 offset:51840
	ds_read_b32 v54, v8 offset:52992
	ds_read_b32 v55, v8 offset:54144
	s_movk_i32 s12, 0xc00
	v_mad_u64_u32 v[8:9], s[12:13], v9, s12, v[6:7]
	v_ashrrev_i32_e32 v9, 31, v8
	v_lshl_add_u64 v[8:9], v[8:9], 2, s[16:17]
	v_add_co_u32_e32 v8, vcc, 0x100000, v8
	s_waitcnt lgkmcnt(14)
	v_add_f32_e32 v1, v1, v10
	v_add_f32_e32 v1, v1, v11
	s_waitcnt lgkmcnt(13)
	v_add_f32_e32 v1, v1, v12
	s_waitcnt lgkmcnt(12)
	v_add_f32_e32 v1, v1, v13
	s_waitcnt lgkmcnt(11)
	v_add_f32_e32 v1, v1, v14
	s_waitcnt lgkmcnt(10)
	v_add_f32_e32 v1, v1, v15
	s_waitcnt lgkmcnt(9)
	v_add_f32_e32 v1, v1, v46
	s_waitcnt lgkmcnt(8)
	v_add_f32_e32 v1, v1, v47
	s_waitcnt lgkmcnt(7)
	v_add_f32_e32 v1, v1, v48
	s_waitcnt lgkmcnt(6)
	v_add_f32_e32 v1, v1, v49
	s_waitcnt lgkmcnt(5)
	v_add_f32_e32 v1, v1, v50
	s_waitcnt lgkmcnt(4)
	v_add_f32_e32 v1, v1, v51
	s_waitcnt lgkmcnt(3)
	v_add_f32_e32 v1, v1, v52
	s_waitcnt lgkmcnt(2)
	v_add_f32_e32 v1, v1, v53
	s_waitcnt lgkmcnt(1)
	v_add_f32_e32 v1, v1, v54
	s_waitcnt lgkmcnt(0)
	v_add_f32_e32 v1, v1, v55
	v_addc_co_u32_e32 v9, vcc, 0, v9, vcc
	global_store_dword v[8:9], v1, off sc1
.LBB0_60:
	s_or_b64 exec, exec, s[34:35]
	s_mov_b32 s12, 0x200000
	s_and_b64 s[4:5], s[4:5], exec
	s_cselect_b32 s4, s12, 0xb00000
	s_add_u32 s12, s16, s4
	s_addc_u32 s13, s17, 0
	s_movk_i32 s4, 0x84
	v_mul_lo_u32 v1, v3, s4
	v_add3_u32 v1, s28, v4, v1
	v_add_u32_e32 v3, 0x400, v1
	s_waitcnt vmcnt(0)
	s_barrier
	v_cmp_eq_u32_e32 vcc, 0, v0
	s_and_saveexec_b64 s[98:99], vcc
	s_cbranch_execz .Lada_pub_done
	v_mov_b32_e32 v145, 0x28000
	v_mov_b32_e32 v146, 1
	global_atomic_add v145, v146, s[16:17]
.Lada_pub_done:
	s_or_b64 exec, exec, s[98:99]
	ds_write2_b32 v1, v5, v7 offset1:66
	ds_write2_b32 v1, v16, v18 offset0:132 offset1:198
	ds_write2_b32 v3, v17, v19 offset0:8 offset1:74
	ds_write2_b32 v3, v20, v21 offset0:140 offset1:206
	v_add_u32_e32 v3, 0x800, v1
	ds_write2_b32 v3, v22, v23 offset0:16 offset1:82
	ds_write2_b32 v3, v24, v26 offset0:148 offset1:214
	v_add_u32_e32 v3, 0xc00, v1
	ds_write2_b32 v3, v25, v27 offset0:24 offset1:90
	ds_write2_b32 v3, v28, v29 offset0:156 offset1:222
	v_add_u32_e32 v3, 0x1000, v1
	ds_write2_b32 v3, v30, v31 offset0:32 offset1:98
	ds_write2_b32 v3, v32, v34 offset0:164 offset1:230
	v_add_u32_e32 v3, 0x1400, v1
	ds_write2_b32 v3, v33, v35 offset0:40 offset1:106
	ds_write2_b32 v3, v36, v37 offset0:172 offset1:238
	v_add_u32_e32 v3, 0x1800, v1
	ds_write2_b32 v3, v38, v39 offset0:48 offset1:114
	ds_write2_b32 v3, v40, v42 offset0:180 offset1:246
	v_add_u32_e32 v1, 0x1c00, v1
	v_lshlrev_b32_e32 v3, 3, v2
	ds_write2_b32 v1, v41, v43 offset0:56 offset1:122
	ds_write2_b32 v1, v44, v45 offset0:188 offset1:254
	v_ashrrev_i32_e32 v1, 3, v2
	v_and_b32_e32 v3, 56, v3
	s_waitcnt lgkmcnt(0)
	v_mul_u32_u24_e32 v6, 0x84, v3
	v_lshlrev_b32_e32 v4, 1, v3
	v_lshlrev_b32_e32 v3, 2, v1
	v_add3_u32 v3, s28, v6, v3
	s_ashr_i32 s31, s30, 31
	ds_read2_b32 v[8:9], v3 offset0:33 offset1:41
	ds_read2_b32 v[10:11], v3 offset1:8
	ds_read2_b32 v[12:13], v3 offset0:66 offset1:74
	ds_read2_b32 v[14:15], v3 offset0:99 offset1:107
	ds_read2_b32 v[16:17], v3 offset0:132 offset1:140
	ds_read2_b32 v[18:19], v3 offset0:165 offset1:173
	ds_read2_b32 v[20:21], v3 offset0:198 offset1:206
	ds_read2_b32 v[22:23], v3 offset0:231 offset1:239
	s_lshl_b64 s[4:5], s[30:31], 1
	s_add_u32 s4, s12, s4
	v_add_u32_e32 v26, s29, v1
	s_addc_u32 s5, s13, s5
	v_mov_b32_e32 v5, 0
	v_ashrrev_i32_e32 v27, 31, v26
	v_lshl_add_u64 v[24:25], s[4:5], 0, v[4:5]
	v_lshlrev_b64 v[28:29], 11, v[26:27]
	s_waitcnt lgkmcnt(6)
	v_cvt_pk_bf16_f32 v4, v10, v8
	s_waitcnt lgkmcnt(4)
	v_cvt_pk_bf16_f32 v5, v12, v14
	s_waitcnt lgkmcnt(2)
	v_cvt_pk_bf16_f32 v6, v16, v18
	s_waitcnt lgkmcnt(0)
	v_cvt_pk_bf16_f32 v7, v20, v22
	v_lshl_add_u64 v[28:29], v[24:25], 0, v[28:29]
	v_add_u32_e32 v8, 8, v26
	global_store_dwordx4 v[28:29], v[4:7], off sc1
	v_cmp_eq_u32_e32 vcc, 0, v0
	s_nop 0
	v_cvt_pk_bf16_f32 v4, v11, v9
	v_ashrrev_i32_e32 v9, 31, v8
	v_cvt_pk_bf16_f32 v5, v13, v15
	v_cvt_pk_bf16_f32 v6, v17, v19
	v_cvt_pk_bf16_f32 v7, v21, v23
	v_lshlrev_b64 v[8:9], 11, v[8:9]
	ds_read2_b32 v[10:11], v3 offset0:49 offset1:57
	ds_read2_b32 v[12:13], v3 offset0:16 offset1:24
	ds_read2_b32 v[14:15], v3 offset0:82 offset1:90
	ds_read2_b32 v[16:17], v3 offset0:115 offset1:123
	ds_read2_b32 v[18:19], v3 offset0:148 offset1:156
	ds_read2_b32 v[20:21], v3 offset0:181 offset1:189
	ds_read2_b32 v[22:23], v3 offset0:214 offset1:222
	ds_read2_b32 v[28:29], v3 offset0:247 offset1:255
	v_lshl_add_u64 v[8:9], v[24:25], 0, v[8:9]
	global_store_dwordx4 v[8:9], v[4:7], off sc1
	v_add_u32_e32 v8, 16, v26
	v_ashrrev_i32_e32 v9, 31, v8
	v_lshlrev_b64 v[8:9], 11, v[8:9]
	s_waitcnt lgkmcnt(6)
	v_cvt_pk_bf16_f32 v4, v12, v10
	s_waitcnt lgkmcnt(4)
	v_cvt_pk_bf16_f32 v5, v14, v16
	s_waitcnt lgkmcnt(2)
	v_cvt_pk_bf16_f32 v6, v18, v20
	s_waitcnt lgkmcnt(0)
	v_cvt_pk_bf16_f32 v7, v22, v28
	v_lshl_add_u64 v[8:9], v[24:25], 0, v[8:9]
	global_store_dwordx4 v[8:9], v[4:7], off sc1
	v_add_u32_e32 v8, 24, v26
	v_ashrrev_i32_e32 v9, 31, v8
	v_lshlrev_b64 v[8:9], 11, v[8:9]
	v_cvt_pk_bf16_f32 v4, v13, v11
	v_cvt_pk_bf16_f32 v5, v15, v17
	v_cvt_pk_bf16_f32 v6, v19, v21
	v_cvt_pk_bf16_f32 v7, v23, v29
	v_lshl_add_u64 v[8:9], v[24:25], 0, v[8:9]
	global_store_dwordx4 v[8:9], v[4:7], off sc1
	s_waitcnt lgkmcnt(0)
	s_waitcnt vmcnt(0)
	s_barrier
	s_and_saveexec_b64 s[4:5], vcc
	s_cbranch_execz .LBB0_65
	s_mov_b64 s[30:31], exec
	v_mbcnt_lo_u32_b32 v1, s30, 0
	v_mbcnt_hi_u32_b32 v1, s31, v1
	v_cmp_eq_u32_e32 vcc, 0, v1
	s_nop 0
	s_waitcnt vmcnt(0)
	s_and_saveexec_b64 s[12:13], vcc
	s_cbranch_execz .LBB0_63
	s_bcnt1_i32_b64 s26, s[30:31]
	v_mov_b32_e32 v1, 0x28000
	v_mov_b32_e32 v3, s26
	s_nop 0
